# FF-IN GEMM: hand-written FFN activation epilogue (DPP-fused fmac, params prefetched to LDS by LDS-DMA in the K-loop instead of serialized global loads)
# speedup vs baseline: 1.0242x; 1.0242x over previous
; #define PG8_LAS __attribute__((address_space(3)))
; #define PG8_STAGE(bufoff, gbase, voff) do { _Pragma("unroll") for (int _i = 0; _i < 2; ++_i) \
;         __builtin_amdgcn_global_load_lds((const unsigned*)((const char*)(gbase) + (voff)[_i]), (PG8_LAS unsigned*)(lds + (bufoff) + ldsw + _i * 8192), 16, 0, 0); } while (0)
; #define PG8_LDA(dst, b, h) do { _Pragma("unroll") for (int m = 0; m < 4; ++m) _Pragma("unroll") for (int k = 0; k < 2; ++k) dst[m][k] = *(const PG8_LAS bf16x8*)(lds + PG8_SA(b, h) + aoff + m * 2048 + k * 1024); } while (0)
; #define PG8_WAIT_V(n) asm volatile("s_waitcnt vmcnt(" #n ")" ::: "memory")
;     __device__ __forceinline__ void operator()(const f32x4 (&acc)[2][2][4][2], const Unit& u, int wr, int wc, int fr, int fq) const {
;     ...
;         const float rs3[2] = {row_rstd(ssq, row0 + 48), row_rstd(ssq, row0 + HALF + 48)};
; #pragma unroll
;         for (int ai = 0; ai < 2; ++ai) { const float rs = rs3[ai];
;             if (fr >= 14) { const f32x4 a = acc[ai][0][3][0] * rs, b = acc[ai][0][3][1] * rs; PG8_LAS f32x4* xp = (PG8_LAS f32x4*)(X + ((wid * 2 + ai) * 2 + (fr - 14)) * 32 + fq * 8); xp[0] = a; xp[1] = b;
;                 if (wr == 1 && ai == 1) { float* g = UH + ((size_t)u.pm * 2 + (fr - 14)) * FF + col; *(f32x4*)g = a; *(f32x4*)(g + 4) = b; } } }
;         asm volatile("s_waitcnt lgkmcnt(0)" ::: "memory"); __builtin_amdgcn_s_barrier(); asm volatile("" ::: "memory");
;         const f32x4 w0a = *(const f32x4*)(cw + col), w0b = *(const f32x4*)(cw + col + 4), w1a = *(const f32x4*)(cw + FF + col), w1b = *(const f32x4*)(cw + FF + col + 4);
;         const f32x4 w2a = *(const f32x4*)(cw + 2 * FF + col), w2b = *(const f32x4*)(cw + 2 * FF + col + 4), ba = *(const f32x4*)(cb + col), bb = *(const f32x4*)(cb + col + 4);
; template <class Epi, class Sched, bool ALIGN_EPI = false, bool SP2 = false>
; __device__ __forceinline__ void gemm_phase(PG8_LAS unsigned char* lds, const Gemm g, const Sched& S, const Epi& E) {
;     ...
;             PG8_LDB(B0, 0, 0); PG8_LDB(B1, 0, 1); PG8_SCHED; PG8_LDA(At, 0, 0); PG8_STAGE(PG8_SA(1, 1), a1 + hstep, voffA);
;             PG8_WAIT_V(8); PG8_WAIT_L(0); PG8_BAR; PG8_MMA(0, 0, At, B0); PG8_MMA(0, 1, At, B1); PG8_BAR; PG8_SCHED;
;             PG8_LDA(At, 0, 1); PG8_STAGE(PG8_SB(0, 0), b2, voffB); PG8_STAGE(PG8_SB(0, 1), b2 + hstep, voffB); PG8_STAGE(PG8_SA(0, 0), a2, voffA);
.LBB0_1247:
	s_add_u32 s44, s8, 0xfffc0080
	s_addc_u32 s45, s9, -1
	s_add_i32 s69, 0, 0x10000
	s_cmp_eq_u32 s68, 12
	s_cselect_b32 s47, s37, s45
	s_cselect_b32 s46, s43, s44
	s_cselect_b32 s45, s35, s67
	s_cselect_b32 s44, s65, s66
	s_add_i32 s72, 0, 0x14000
	s_cmp_lg_u32 s68, 0
	s_cbranch_scc1 .Lffin_nopf
	s_cmp_lt_u32 s52, 0x1000
	s_cbranch_scc0 .Lffin_pf_w
	s_lshl_b32 s98, s42, 12
	s_add_u32 s98, s12, s98
	s_addc_u32 s99, s13, 0
	v_lshlrev_b32_e32 v232, 4, v174
	s_add_i32 m0, s52, 0x21000
	s_nop 0
	global_load_lds_dwordx4 v232, s[98:99]
	s_branch .Lffin_nopf
.Lffin_pf_w:
	s_lshr_b32 s100, s52, 10
	s_sub_u32 s100, s100, 4
	s_mov_b64 s[98:99], s[18:19]
	s_cmp_eq_u32 s100, 1
	s_cselect_b32 s98, s26, s98
	s_cselect_b32 s99, s27, s99
	s_cmp_eq_u32 s100, 2
	s_cselect_b32 s98, s28, s98
	s_cselect_b32 s99, s29, s99
	s_cmp_eq_u32 s100, 3
	s_cselect_b32 s98, s10, s98
	s_cselect_b32 s99, s11, s99
	s_lshl_b32 s101, s33, 9
	s_add_u32 s98, s98, s101
	s_addc_u32 s99, s99, 0
	v_and_b32_e32 v232, 31, v225
	v_lshlrev_b32_e32 v232, 4, v232
	s_lshl_b32 s100, s100, 10
	s_add_i32 m0, s100, 0x22000
	s_nop 0
	global_load_lds_dwordx4 v232, s[98:99]
.Lffin_nopf:
	v_add_u32_e32 v118, s69, v229
	v_add_u32_e32 v134, s72, v229
	ds_read_b128 v[106:109], v118
	ds_read_b128 v[110:113], v118 offset:1024
	ds_read_b128 v[114:117], v118 offset:2048
	ds_read_b128 v[118:121], v118 offset:3072
	ds_read_b128 v[122:125], v134
	ds_read_b128 v[126:129], v134 offset:1024
	ds_read_b128 v[130:133], v134 offset:2048
	ds_read_b128 v[134:137], v134 offset:3072
	v_lshl_add_u64 v[212:213], s[8:9], 0, v[188:189]
	s_add_i32 m0, s53, 0xc000
	ds_read_b128 v[162:165], v230
	ds_read_b128 v[166:169], v230 offset:1024
	ds_read_b128 v[170:173], v230 offset:2048
	ds_read_b128 v[192:195], v230 offset:3072
	ds_read_b128 v[196:199], v230 offset:4096
	ds_read_b128 v[200:203], v230 offset:5120
	ds_read_b128 v[204:207], v230 offset:6144
	ds_read_b128 v[208:211], v230 offset:7168
	global_load_lds_dwordx4 v[212:213], off
	v_lshl_add_u64 v[212:213], s[8:9], 0, v[190:191]
	s_add_i32 m0, s53, 0xe000
	s_nop 0
	global_load_lds_dwordx4 v[212:213], off
	s_waitcnt vmcnt(8)
	s_waitcnt lgkmcnt(0)
	s_barrier
	s_setprio 1
	s_waitcnt lgkmcnt(0)
	v_mfma_f32_16x16x32_bf16 v[158:161], v[106:109], v[162:165], v[158:161]
	v_mfma_f32_16x16x32_bf16 v[154:157], v[114:117], v[162:165], v[154:157]
	v_mfma_f32_16x16x32_bf16 v[142:145], v[106:109], v[170:173], v[142:145]
	v_mfma_f32_16x16x32_bf16 v[138:141], v[114:117], v[170:173], v[138:141]
	v_mfma_f32_16x16x32_bf16 v[94:97], v[106:109], v[196:199], v[94:97]
	v_mfma_f32_16x16x32_bf16 v[90:93], v[114:117], v[196:199], v[90:93]
	v_mfma_f32_16x16x32_bf16 v[78:81], v[106:109], v[204:207], v[78:81]
	v_mfma_f32_16x16x32_bf16 v[74:77], v[114:117], v[204:207], v[74:77]
	v_mfma_f32_16x16x32_bf16 v[158:161], v[110:113], v[166:169], v[158:161]
	v_mfma_f32_16x16x32_bf16 v[154:157], v[118:121], v[166:169], v[154:157]
	v_mfma_f32_16x16x32_bf16 v[142:145], v[110:113], v[192:195], v[142:145]
	v_mfma_f32_16x16x32_bf16 v[138:141], v[118:121], v[192:195], v[138:141]
	v_mfma_f32_16x16x32_bf16 v[94:97], v[110:113], v[200:203], v[94:97]
	v_mfma_f32_16x16x32_bf16 v[90:93], v[118:121], v[200:203], v[90:93]
	v_mfma_f32_16x16x32_bf16 v[78:81], v[110:113], v[208:211], v[78:81]
	v_mfma_f32_16x16x32_bf16 v[74:77], v[118:121], v[208:211], v[74:77]
	s_setprio 0
	s_setprio 1
	v_mfma_f32_16x16x32_bf16 v[150:153], v[122:125], v[162:165], v[150:153]
	v_mfma_f32_16x16x32_bf16 v[146:149], v[130:133], v[162:165], v[146:149]
	v_mfma_f32_16x16x32_bf16 v[102:105], v[122:125], v[170:173], v[102:105]
	v_mfma_f32_16x16x32_bf16 v[98:101], v[130:133], v[170:173], v[98:101]
	v_mfma_f32_16x16x32_bf16 v[86:89], v[122:125], v[196:199], v[86:89]
	v_mfma_f32_16x16x32_bf16 v[82:85], v[130:133], v[196:199], v[82:85]
	v_mfma_f32_16x16x32_bf16 v[70:73], v[122:125], v[204:207], v[70:73]
	v_mfma_f32_16x16x32_bf16 v[66:69], v[130:133], v[204:207], v[66:69]
	v_mfma_f32_16x16x32_bf16 v[150:153], v[126:129], v[166:169], v[150:153]
	v_mfma_f32_16x16x32_bf16 v[146:149], v[134:137], v[166:169], v[146:149]
	v_mfma_f32_16x16x32_bf16 v[102:105], v[126:129], v[192:195], v[102:105]
	v_mfma_f32_16x16x32_bf16 v[98:101], v[134:137], v[192:195], v[98:101]
	v_mfma_f32_16x16x32_bf16 v[86:89], v[126:129], v[200:203], v[86:89]
	v_mfma_f32_16x16x32_bf16 v[82:85], v[134:137], v[200:203], v[82:85]
	v_mfma_f32_16x16x32_bf16 v[70:73], v[126:129], v[208:211], v[70:73]
	v_mfma_f32_16x16x32_bf16 v[66:69], v[134:137], v[208:211], v[66:69]
	s_setprio 0
	s_barrier
	s_add_i32 s69, s69, s52
	v_lshl_add_u64 v[212:213], s[44:45], 0, v[184:185]
	s_mov_b32 m0, s69
	ds_read_b128 v[162:165], v230 offset:16384
	ds_read_b128 v[166:169], v230 offset:17408
	ds_read_b128 v[170:173], v230 offset:18432
	ds_read_b128 v[192:195], v230 offset:19456
	ds_read_b128 v[196:199], v230 offset:20480
	ds_read_b128 v[200:203], v230 offset:21504
	ds_read_b128 v[204:207], v230 offset:22528
	ds_read_b128 v[208:211], v230 offset:23552
	global_load_lds_dwordx4 v[212:213], off
	s_add_i32 m0, s69, 0x2000
	s_add_u32 s70, s44, 0x40000
	v_lshl_add_u64 v[214:215], s[44:45], 0, v[180:181]
	s_addc_u32 s71, s45, 0
	s_add_i32 s69, s72, s52
	global_load_lds_dwordx4 v[214:215], off
	v_lshl_add_u64 v[216:217], s[70:71], 0, v[184:185]
	s_mov_b32 m0, s69
	v_lshl_add_u64 v[218:219], s[46:47], 0, v[182:183]
	global_load_lds_dwordx4 v[216:217], off
	v_lshl_add_u64 v[216:217], s[70:71], 0, v[180:181]
	s_add_i32 m0, s69, 0x2000
	s_nop 0
	global_load_lds_dwordx4 v[216:217], off
	v_lshl_add_u64 v[216:217], s[46:47], 0, v[186:187]
	s_mov_b32 m0, s53
	s_nop 0
	global_load_lds_dwordx4 v[216:217], off
	s_mov_b32 m0, s54
	s_nop 0
	global_load_lds_dwordx4 v[218:219], off
	s_waitcnt vmcnt(8)
	s_waitcnt lgkmcnt(0)
	s_barrier
; #define PG8_STAGE(bufoff, gbase, voff) do { _Pragma("unroll") for (int _i = 0; _i < 2; ++_i) \
;         __builtin_amdgcn_global_load_lds((const unsigned*)((const char*)(gbase) + (voff)[_i]), (PG8_LAS unsigned*)(lds + (bufoff) + ldsw + _i * 8192), 16, 0, 0); } while (0)
; #define PG8_LDA(dst, b, h) do { _Pragma("unroll") for (int m = 0; m < 4; ++m) _Pragma("unroll") for (int k = 0; k < 2; ++k) dst[m][k] = *(const PG8_LAS bf16x8*)(lds + PG8_SA(b, h) + aoff + m * 2048 + k * 1024); } while (0)
; #define PG8_LDB(dst, b, h) do { _Pragma("unroll") for (int n = 0; n < 2; ++n) _Pragma("unroll") for (int k = 0; k < 2; ++k) dst[n][k] = *(const PG8_LAS bf16x8*)(lds + PG8_SB(b, h) + boff + n * 2048 + k * 1024); } while (0)
; #define PG8_MMA(ai, bj, At, Bt) do { __builtin_amdgcn_s_setprio(1); _Pragma("unroll") for (int m = 0; m < 4; ++m) _Pragma("unroll") for (int n = 0; n < 2; ++n) _Pragma("unroll") for (int k = 0; k < 2; ++k) \
;         acc[ai][bj][m][n] = __builtin_amdgcn_mfma_f32_16x16x32_bf16(Bt[n][k], At[m][k], acc[ai][bj][m][n], 0, 0, 0); __builtin_amdgcn_s_setprio(0); } while (0)
; #define PG8_WAIT_V(n) asm volatile("s_waitcnt vmcnt(" #n ")" ::: "memory")
; #define PG8_WAIT_L(n) asm volatile("s_waitcnt lgkmcnt(" #n ")" ::: "memory")
; #define PG8_BAR __builtin_amdgcn_s_barrier()
; #define PG8_SCHED __builtin_amdgcn_sched_barrier(0)
; template <class Epi, class Sched, bool ALIGN_EPI = false, bool SP2 = false>
; __device__ __forceinline__ void gemm_phase(PG8_LAS unsigned char* lds, const Gemm g, const Sched& S, const Epi& E) {
;     ...
;             PG8_WAIT_V(8); PG8_WAIT_L(0); PG8_BAR; PG8_MMA(0, 0, At, B0); PG8_MMA(0, 1, At, B1); PG8_BAR; PG8_SCHED;
;             PG8_LDA(At, 0, 1); PG8_STAGE(PG8_SB(0, 0), b2, voffB); PG8_STAGE(PG8_SB(0, 1), b2 + hstep, voffB); PG8_STAGE(PG8_SA(0, 0), a2, voffA);
;             PG8_WAIT_V(8); PG8_WAIT_L(0); PG8_BAR; PG8_MMA(1, 0, At, B0); PG8_MMA(1, 1, At, B1); PG8_BAR; PG8_SCHED;
;             PG8_LDB(B0, 1, 0); PG8_LDB(B1, 1, 1); PG8_SCHED; PG8_LDA(At, 1, 0); PG8_STAGE(PG8_SA(0, 1), a2 + hstep, voffA);
;             PG8_WAIT_V(8); PG8_WAIT_L(0); PG8_BAR; PG8_MMA(0, 0, At, B0); PG8_MMA(0, 1, At, B1); PG8_BAR; PG8_SCHED;
	s_setprio 1
	s_waitcnt lgkmcnt(0)
	v_mfma_f32_16x16x32_bf16 v[62:65], v[106:109], v[162:165], v[62:65]
	v_mfma_f32_16x16x32_bf16 v[58:61], v[114:117], v[162:165], v[58:61]
	v_mfma_f32_16x16x32_bf16 v[46:49], v[106:109], v[170:173], v[46:49]
	v_mfma_f32_16x16x32_bf16 v[42:45], v[114:117], v[170:173], v[42:45]
	v_mfma_f32_16x16x32_bf16 v[30:33], v[106:109], v[196:199], v[30:33]
	v_mfma_f32_16x16x32_bf16 v[26:29], v[114:117], v[196:199], v[26:29]
	v_mfma_f32_16x16x32_bf16 v[14:17], v[106:109], v[204:207], v[14:17]
	v_mfma_f32_16x16x32_bf16 v[10:13], v[114:117], v[204:207], v[10:13]
	v_mfma_f32_16x16x32_bf16 v[62:65], v[110:113], v[166:169], v[62:65]
	v_mfma_f32_16x16x32_bf16 v[58:61], v[118:121], v[166:169], v[58:61]
	v_mfma_f32_16x16x32_bf16 v[46:49], v[110:113], v[192:195], v[46:49]
	v_mfma_f32_16x16x32_bf16 v[42:45], v[118:121], v[192:195], v[42:45]
	v_mfma_f32_16x16x32_bf16 v[30:33], v[110:113], v[200:203], v[30:33]
	v_mfma_f32_16x16x32_bf16 v[26:29], v[118:121], v[200:203], v[26:29]
	v_mfma_f32_16x16x32_bf16 v[14:17], v[110:113], v[208:211], v[14:17]
	v_mfma_f32_16x16x32_bf16 v[10:13], v[118:121], v[208:211], v[10:13]
	s_setprio 0
	s_setprio 1
	v_mfma_f32_16x16x32_bf16 v[54:57], v[122:125], v[162:165], v[54:57]
	v_mfma_f32_16x16x32_bf16 v[50:53], v[130:133], v[162:165], v[50:53]
	v_mfma_f32_16x16x32_bf16 v[38:41], v[122:125], v[170:173], v[38:41]
	v_mfma_f32_16x16x32_bf16 v[34:37], v[130:133], v[170:173], v[34:37]
	v_mfma_f32_16x16x32_bf16 v[22:25], v[122:125], v[196:199], v[22:25]
	v_mfma_f32_16x16x32_bf16 v[18:21], v[130:133], v[196:199], v[18:21]
	v_mfma_f32_16x16x32_bf16 v[6:9], v[122:125], v[204:207], v[6:9]
	v_mfma_f32_16x16x32_bf16 v[2:5], v[130:133], v[204:207], v[2:5]
	v_mfma_f32_16x16x32_bf16 v[54:57], v[126:129], v[166:169], v[54:57]
	v_mfma_f32_16x16x32_bf16 v[50:53], v[134:137], v[166:169], v[50:53]
	v_mfma_f32_16x16x32_bf16 v[38:41], v[126:129], v[192:195], v[38:41]
	v_mfma_f32_16x16x32_bf16 v[34:37], v[134:137], v[192:195], v[34:37]
	v_mfma_f32_16x16x32_bf16 v[22:25], v[126:129], v[200:203], v[22:25]
	v_mfma_f32_16x16x32_bf16 v[18:21], v[134:137], v[200:203], v[18:21]
	v_mfma_f32_16x16x32_bf16 v[6:9], v[126:129], v[208:211], v[6:9]
	v_mfma_f32_16x16x32_bf16 v[2:5], v[134:137], v[208:211], v[2:5]
	s_setprio 0
	s_barrier
	s_add_i32 s69, 0, 0x18000
	s_add_i32 s70, 0, 0x1c000
	v_add_u32_e32 v118, s69, v229
	v_add_u32_e32 v134, s70, v229
	ds_read_b128 v[106:109], v118
	ds_read_b128 v[110:113], v118 offset:1024
	ds_read_b128 v[114:117], v118 offset:2048
	ds_read_b128 v[118:121], v118 offset:3072
	ds_read_b128 v[122:125], v134
	ds_read_b128 v[126:129], v134 offset:1024
	ds_read_b128 v[130:133], v134 offset:2048
	ds_read_b128 v[134:137], v134 offset:3072
	s_add_u32 s46, s46, 0x40000
	s_addc_u32 s47, s47, 0
	s_mov_b32 m0, s55
	v_lshl_add_u64 v[220:221], s[46:47], 0, v[186:187]
	ds_read_b128 v[162:165], v230 offset:32768
	ds_read_b128 v[166:169], v230 offset:33792
	ds_read_b128 v[170:173], v230 offset:34816
	ds_read_b128 v[192:195], v230 offset:35840
	ds_read_b128 v[196:199], v230 offset:36864
	ds_read_b128 v[200:203], v230 offset:37888
	ds_read_b128 v[204:207], v230 offset:38912
	ds_read_b128 v[208:211], v230 offset:39936
	global_load_lds_dwordx4 v[220:221], off
	v_lshl_add_u64 v[220:221], s[46:47], 0, v[182:183]
	s_mov_b32 m0, s56
	s_nop 0
	global_load_lds_dwordx4 v[220:221], off
	s_waitcnt vmcnt(8)
	s_waitcnt lgkmcnt(0)
	s_barrier
	s_setprio 1
	s_waitcnt lgkmcnt(0)
	v_mfma_f32_16x16x32_bf16 v[158:161], v[106:109], v[162:165], v[158:161]
	v_mfma_f32_16x16x32_bf16 v[154:157], v[114:117], v[162:165], v[154:157]
	v_mfma_f32_16x16x32_bf16 v[142:145], v[106:109], v[170:173], v[142:145]
	v_mfma_f32_16x16x32_bf16 v[138:141], v[114:117], v[170:173], v[138:141]
	v_mfma_f32_16x16x32_bf16 v[94:97], v[106:109], v[196:199], v[94:97]
	v_mfma_f32_16x16x32_bf16 v[90:93], v[114:117], v[196:199], v[90:93]
	v_mfma_f32_16x16x32_bf16 v[78:81], v[106:109], v[204:207], v[78:81]
	v_mfma_f32_16x16x32_bf16 v[74:77], v[114:117], v[204:207], v[74:77]
	v_mfma_f32_16x16x32_bf16 v[158:161], v[110:113], v[166:169], v[158:161]
	v_mfma_f32_16x16x32_bf16 v[154:157], v[118:121], v[166:169], v[154:157]
	v_mfma_f32_16x16x32_bf16 v[142:145], v[110:113], v[192:195], v[142:145]
	v_mfma_f32_16x16x32_bf16 v[138:141], v[118:121], v[192:195], v[138:141]
	v_mfma_f32_16x16x32_bf16 v[94:97], v[110:113], v[200:203], v[94:97]
	v_mfma_f32_16x16x32_bf16 v[90:93], v[118:121], v[200:203], v[90:93]
	v_mfma_f32_16x16x32_bf16 v[78:81], v[110:113], v[208:211], v[78:81]
	v_mfma_f32_16x16x32_bf16 v[74:77], v[118:121], v[208:211], v[74:77]
	s_setprio 0
	s_setprio 1
	v_mfma_f32_16x16x32_bf16 v[150:153], v[122:125], v[162:165], v[150:153]
	v_mfma_f32_16x16x32_bf16 v[146:149], v[130:133], v[162:165], v[146:149]
	v_mfma_f32_16x16x32_bf16 v[102:105], v[122:125], v[170:173], v[102:105]
	v_mfma_f32_16x16x32_bf16 v[98:101], v[130:133], v[170:173], v[98:101]
	v_mfma_f32_16x16x32_bf16 v[86:89], v[122:125], v[196:199], v[86:89]
	v_mfma_f32_16x16x32_bf16 v[82:85], v[130:133], v[196:199], v[82:85]
	v_mfma_f32_16x16x32_bf16 v[70:73], v[122:125], v[204:207], v[70:73]
	v_mfma_f32_16x16x32_bf16 v[66:69], v[130:133], v[204:207], v[66:69]
	v_mfma_f32_16x16x32_bf16 v[150:153], v[126:129], v[166:169], v[150:153]
	v_mfma_f32_16x16x32_bf16 v[146:149], v[134:137], v[166:169], v[146:149]
	v_mfma_f32_16x16x32_bf16 v[102:105], v[126:129], v[192:195], v[102:105]
	v_mfma_f32_16x16x32_bf16 v[98:101], v[134:137], v[192:195], v[98:101]
	v_mfma_f32_16x16x32_bf16 v[86:89], v[126:129], v[200:203], v[86:89]
	v_mfma_f32_16x16x32_bf16 v[82:85], v[134:137], v[200:203], v[82:85]
	v_mfma_f32_16x16x32_bf16 v[70:73], v[126:129], v[208:211], v[70:73]
	v_mfma_f32_16x16x32_bf16 v[66:69], v[134:137], v[208:211], v[66:69]
	s_setprio 0
	s_barrier
; #define PG8_LAS __attribute__((address_space(3)))
;     __device__ __forceinline__ void operator()(const f32x4 (&acc)[2][2][4][2], const Unit& u, int wr, int wc, int fr, int fq) const {
;     ...
;         const int wid = wr * 4 + wc, cl = 32 * wc + 8 * fq, col = u.pn * 128 + cl, row0 = u.pm * BM + wr * 64 + fr;
;         const float rs3[2] = {row_rstd(ssq, row0 + 48), row_rstd(ssq, row0 + HALF + 48)};
; #pragma unroll
;         for (int ai = 0; ai < 2; ++ai) { const float rs = rs3[ai];
;             if (fr >= 14) { const f32x4 a = acc[ai][0][3][0] * rs, b = acc[ai][0][3][1] * rs; PG8_LAS f32x4* xp = (PG8_LAS f32x4*)(X + ((wid * 2 + ai) * 2 + (fr - 14)) * 32 + fq * 8); xp[0] = a; xp[1] = b;
;                 if (wr == 1 && ai == 1) { float* g = UH + ((size_t)u.pm * 2 + (fr - 14)) * FF + col; *(f32x4*)g = a; *(f32x4*)(g + 4) = b; } } }
;         asm volatile("s_waitcnt lgkmcnt(0)" ::: "memory"); __builtin_amdgcn_s_barrier(); asm volatile("" ::: "memory");
;         const f32x4 w0a = *(const f32x4*)(cw + col), w0b = *(const f32x4*)(cw + col + 4), w1a = *(const f32x4*)(cw + FF + col), w1b = *(const f32x4*)(cw + FF + col + 4);
;         const f32x4 w2a = *(const f32x4*)(cw + 2 * FF + col), w2b = *(const f32x4*)(cw + 2 * FF + col + 4), ba = *(const f32x4*)(cb + col), bb = *(const f32x4*)(cb + col + 4);
;         const float m0 = (fr == 0) ? 1.f : 0.f, m1 = (fr == 1) ? 1.f : 0.f;
; #pragma unroll
;         for (int ai = 0; ai < 2; ++ai) {
;             f32x4 pa = {0.f, 0.f, 0.f, 0.f}, pb = {0.f, 0.f, 0.f, 0.f};
;             float rsv[4];
; #pragma unroll
;             for (int m = 0; m < 4; ++m) rsv[m] = row_rstd(ssq, row0 + ai * HALF + m * 16);
	s_add_i32 s46, s69, s52
	v_lshl_add_u64 v[212:213], v[212:213], 0, s[96:97]
	s_mov_b32 m0, s46
	ds_read_b128 v[162:165], v230 offset:49152
	ds_read_b128 v[166:169], v230 offset:50176
	ds_read_b128 v[170:173], v230 offset:51200
	ds_read_b128 v[192:195], v230 offset:52224
	ds_read_b128 v[196:199], v230 offset:53248
	ds_read_b128 v[200:203], v230 offset:54272
	ds_read_b128 v[204:207], v230 offset:55296
	ds_read_b128 v[208:211], v230 offset:56320
	global_load_lds_dwordx4 v[212:213], off
	s_add_i32 m0, s46, 0x2000
	s_add_u32 s44, s44, 0x40080
	v_lshl_add_u64 v[212:213], v[214:215], 0, s[96:97]
	s_addc_u32 s45, s45, 0
	s_add_i32 s46, s70, s52
	global_load_lds_dwordx4 v[212:213], off
	v_lshl_add_u64 v[212:213], s[44:45], 0, v[184:185]
	s_mov_b32 m0, s46
	s_nop 0
	global_load_lds_dwordx4 v[212:213], off
	v_lshl_add_u64 v[212:213], s[44:45], 0, v[180:181]
	s_add_i32 m0, s46, 0x2000
	s_nop 0
	global_load_lds_dwordx4 v[212:213], off
	v_lshl_add_u64 v[212:213], v[216:217], 0, s[96:97]
	s_mov_b32 m0, s60
	s_nop 0
	global_load_lds_dwordx4 v[212:213], off
	v_lshl_add_u64 v[212:213], v[218:219], 0, s[96:97]
	s_mov_b32 m0, s61
	s_nop 0
	global_load_lds_dwordx4 v[212:213], off
	s_waitcnt vmcnt(8)
	s_waitcnt lgkmcnt(0)
	s_barrier
	s_setprio 1
	s_waitcnt lgkmcnt(0)
	v_mfma_f32_16x16x32_bf16 v[62:65], v[106:109], v[162:165], v[62:65]
	v_mfma_f32_16x16x32_bf16 v[58:61], v[114:117], v[162:165], v[58:61]
	v_mfma_f32_16x16x32_bf16 v[46:49], v[106:109], v[170:173], v[46:49]
	v_mfma_f32_16x16x32_bf16 v[42:45], v[114:117], v[170:173], v[42:45]
	v_mfma_f32_16x16x32_bf16 v[30:33], v[106:109], v[196:199], v[30:33]
	v_mfma_f32_16x16x32_bf16 v[26:29], v[114:117], v[196:199], v[26:29]
	v_mfma_f32_16x16x32_bf16 v[14:17], v[106:109], v[204:207], v[14:17]
	v_mfma_f32_16x16x32_bf16 v[10:13], v[114:117], v[204:207], v[10:13]
	v_mfma_f32_16x16x32_bf16 v[62:65], v[110:113], v[166:169], v[62:65]
	v_mfma_f32_16x16x32_bf16 v[58:61], v[118:121], v[166:169], v[58:61]
	v_mfma_f32_16x16x32_bf16 v[46:49], v[110:113], v[192:195], v[46:49]
	v_mfma_f32_16x16x32_bf16 v[42:45], v[118:121], v[192:195], v[42:45]
	v_mfma_f32_16x16x32_bf16 v[30:33], v[110:113], v[200:203], v[30:33]
	v_mfma_f32_16x16x32_bf16 v[26:29], v[118:121], v[200:203], v[26:29]
	v_mfma_f32_16x16x32_bf16 v[14:17], v[110:113], v[208:211], v[14:17]
	v_mfma_f32_16x16x32_bf16 v[10:13], v[118:121], v[208:211], v[10:13]
	s_setprio 0
	s_setprio 1
	v_mfma_f32_16x16x32_bf16 v[54:57], v[122:125], v[162:165], v[54:57]
	v_mfma_f32_16x16x32_bf16 v[50:53], v[130:133], v[162:165], v[50:53]
	v_mfma_f32_16x16x32_bf16 v[38:41], v[122:125], v[170:173], v[38:41]
	v_mfma_f32_16x16x32_bf16 v[34:37], v[130:133], v[170:173], v[34:37]
	v_mfma_f32_16x16x32_bf16 v[22:25], v[122:125], v[196:199], v[22:25]
	v_mfma_f32_16x16x32_bf16 v[18:21], v[130:133], v[196:199], v[18:21]
	v_mfma_f32_16x16x32_bf16 v[6:9], v[122:125], v[204:207], v[6:9]
	v_mfma_f32_16x16x32_bf16 v[2:5], v[130:133], v[204:207], v[2:5]
	v_mfma_f32_16x16x32_bf16 v[54:57], v[126:129], v[166:169], v[54:57]
	v_mfma_f32_16x16x32_bf16 v[50:53], v[134:137], v[166:169], v[50:53]
	v_mfma_f32_16x16x32_bf16 v[38:41], v[126:129], v[192:195], v[38:41]
	v_mfma_f32_16x16x32_bf16 v[34:37], v[134:137], v[192:195], v[34:37]
	v_mfma_f32_16x16x32_bf16 v[22:25], v[126:129], v[200:203], v[22:25]
	v_mfma_f32_16x16x32_bf16 v[18:21], v[134:137], v[200:203], v[18:21]
	v_mfma_f32_16x16x32_bf16 v[6:9], v[126:129], v[208:211], v[6:9]
	v_mfma_f32_16x16x32_bf16 v[2:5], v[134:137], v[208:211], v[2:5]
	s_setprio 0
	s_barrier
	s_add_i32 s68, s68, 2
	s_add_u32 s8, s8, 0x100
	s_addc_u32 s9, s9, 0
	s_add_u32 s66, s66, 0x100
	s_addc_u32 s67, s67, 0
	s_cmp_gt_u32 s68, 13
	s_cbranch_scc0 .LBB0_1247
	s_and_b64 vcc, exec, s[24:25]
	s_cbranch_vccz .LBB0_1250
	s_barrier
.LBB0_1250:
	v_lshlrev_b32_e32 v163, 3, v228
	v_add_u32_e32 v165, s59, v163
	v_add_u32_e32 v167, s58, v1
	v_lshlrev_b32_e32 v171, 4, v167
	v_add_u32_e32 v171, 0x21000, v171
	v_lshlrev_b32_e32 v173, 2, v165
	v_add_u32_e32 v173, 0x22000, v173
	ds_read_b128 v[192:195], v171
	ds_read_b128 v[196:199], v171 offset:256
	ds_read_b128 v[200:203], v171 offset:512
	ds_read_b128 v[204:207], v171 offset:768
	ds_read_b128 v[208:211], v171 offset:2048
	ds_read_b128 v[212:215], v171 offset:2304
	ds_read_b128 v[216:219], v171 offset:2560
	ds_read_b128 v[220:223], v171 offset:2816
	ds_read_b128 v[106:109], v173
	ds_read_b128 v[110:113], v173 offset:16
	ds_read_b128 v[114:117], v173 offset:1024
	ds_read_b128 v[118:121], v173 offset:1040
	ds_read_b128 v[122:125], v173 offset:2048
	ds_read_b128 v[126:129], v173 offset:2064
	ds_read_b128 v[130:133], v173 offset:3072
	s_waitcnt lgkmcnt(14)
	ds_read_b128 v[134:137], v173 offset:3088
	s_lshl_b32 s44, s33, 7
	v_add_u32_e32 v169, s44, v165
	s_lshl_b32 s45, s42, 8
	v_add_u32_e32 v167, s45, v167
	s_waitcnt lgkmcnt(15)
	v_add_f32_e32 v192, v192, v193
	v_add_f32_e32 v194, v194, v195
	s_waitcnt lgkmcnt(14)
	v_add_f32_e32 v196, v196, v197
	v_add_f32_e32 v198, v198, v199
	s_waitcnt lgkmcnt(13)
	v_add_f32_e32 v200, v200, v201
	v_add_f32_e32 v202, v202, v203
	s_waitcnt lgkmcnt(12)
	v_add_f32_e32 v204, v204, v205
	v_add_f32_e32 v206, v206, v207
	s_waitcnt lgkmcnt(11)
	v_add_f32_e32 v208, v208, v209
	v_add_f32_e32 v210, v210, v211
	s_waitcnt lgkmcnt(10)
	v_add_f32_e32 v212, v212, v213
	v_add_f32_e32 v214, v214, v215
	s_waitcnt lgkmcnt(9)
	v_add_f32_e32 v216, v216, v217
	v_add_f32_e32 v218, v218, v219
	s_waitcnt lgkmcnt(8)
; #define PG8_LAS __attribute__((address_space(3)))
;     __device__ __forceinline__ void operator()(const f32x4 (&acc)[2][2][4][2], const Unit& u, int wr, int wc, int fr, int fq) const {
;     ...
;         const float rs3[2] = {row_rstd(ssq, row0 + 48), row_rstd(ssq, row0 + HALF + 48)};
; #pragma unroll
;         for (int ai = 0; ai < 2; ++ai) { const float rs = rs3[ai];
;             if (fr >= 14) { const f32x4 a = acc[ai][0][3][0] * rs, b = acc[ai][0][3][1] * rs; PG8_LAS f32x4* xp = (PG8_LAS f32x4*)(X + ((wid * 2 + ai) * 2 + (fr - 14)) * 32 + fq * 8); xp[0] = a; xp[1] = b;
;                 if (wr == 1 && ai == 1) { float* g = UH + ((size_t)u.pm * 2 + (fr - 14)) * FF + col; *(f32x4*)g = a; *(f32x4*)(g + 4) = b; } } }
;         asm volatile("s_waitcnt lgkmcnt(0)" ::: "memory"); __builtin_amdgcn_s_barrier(); asm volatile("" ::: "memory");
;         const f32x4 w0a = *(const f32x4*)(cw + col), w0b = *(const f32x4*)(cw + col + 4), w1a = *(const f32x4*)(cw + FF + col), w1b = *(const f32x4*)(cw + FF + col + 4);
;         const f32x4 w2a = *(const f32x4*)(cw + 2 * FF + col), w2b = *(const f32x4*)(cw + 2 * FF + col + 4), ba = *(const f32x4*)(cb + col), bb = *(const f32x4*)(cb + col + 4);
;         const float m0 = (fr == 0) ? 1.f : 0.f, m1 = (fr == 1) ? 1.f : 0.f;
; #pragma unroll
;         for (int ai = 0; ai < 2; ++ai) {
;             f32x4 pa = {0.f, 0.f, 0.f, 0.f}, pb = {0.f, 0.f, 0.f, 0.f};
;             float rsv[4];
; #pragma unroll
;             for (int m = 0; m < 4; ++m) rsv[m] = row_rstd(ssq, row0 + ai * HALF + m * 16);
; #pragma unroll
;             for (int m = 0; m < 4; ++m) {
;                 const int row = row0 + ai * HALF + m * 16; const float rs = rsv[m];
;                 const f32x4 ca = acc[ai][0][m][0] * rs, cb_ = acc[ai][0][m][1] * rs;
;                 f32x4 aa = w2a * ca + ba, ab = w2b * cb_ + bb;
; #pragma unroll
;                 for (int c = 0; c < 4; ++c) { aa[c] = __builtin_fmaf(w1a[c], dpp_shr1(ca[c]), aa[c]); ab[c] = __builtin_fmaf(w1b[c], dpp_shr1(cb_[c]), ab[c]);
;                     aa[c] = __builtin_fmaf(w0a[c], dpp_shr2(ca[c]), aa[c]); ab[c] = __builtin_fmaf(w0b[c], dpp_shr2(cb_[c]), ab[c]); }
;                 if (m == 0) {
;                     if (ai == 1 || wr == 1) { const int sw = ((ai == 1 && wr == 0) ? 4 : 0) + wc, sai = (ai == 1 && wr == 1) ? 1 : 0;
	v_add_f32_e32 v220, v220, v221
	v_add_f32_e32 v222, v222, v223
	v_add_f32_e32 v192, v192, v194
	v_add_f32_e32 v196, v196, v198
	v_add_f32_e32 v200, v200, v202
	v_add_f32_e32 v204, v204, v206
	v_add_f32_e32 v208, v208, v210
	v_add_f32_e32 v212, v212, v214
	v_add_f32_e32 v216, v216, v218
	v_add_f32_e32 v220, v220, v222
	v_fmamk_f32 v192, v192, 0x3a800000, v175
	v_fmamk_f32 v196, v196, 0x3a800000, v175
	v_fmamk_f32 v200, v200, 0x3a800000, v175
	v_fmamk_f32 v204, v204, 0x3a800000, v175
	v_fmamk_f32 v208, v208, 0x3a800000, v175
	v_fmamk_f32 v212, v212, 0x3a800000, v175
	v_fmamk_f32 v216, v216, 0x3a800000, v175
	v_fmamk_f32 v220, v220, 0x3a800000, v175
	v_rsq_f32_e32 v162, v192
	v_rsq_f32_e32 v164, v196
	v_rsq_f32_e32 v166, v200
	v_rsq_f32_e32 v168, v204
	v_rsq_f32_e32 v170, v208
	v_rsq_f32_e32 v172, v212
	v_rsq_f32_e32 v232, v216
	v_rsq_f32_e32 v234, v220
	s_waitcnt lgkmcnt(0)
	v_mov_b64_e32 v[220:221], s[14:15]
	v_mad_u64_u32 v[220:221], s[46:47], v167, s84, v[220:221]
	v_lshlrev_b32_e32 v167, 1, v169
	s_mov_b64 s[100:101], 0x16000
	s_mov_b64 s[98:99], 0x6e000
	s_nop 0
	v_add_co_u32_e32 v220, vcc, v220, v167
	s_nop 1
	v_addc_co_u32_e32 v221, vcc, 0, v221, vcc
	v_pk_mul_f32 v[78:79], v[78:79], v[168:169] op_sel_hi:[1,0]
	v_pk_mul_f32 v[80:81], v[80:81], v[168:169] op_sel_hi:[1,0]
	v_pk_mul_f32 v[74:75], v[74:75], v[168:169] op_sel_hi:[1,0]
	v_pk_mul_f32 v[76:77], v[76:77], v[168:169] op_sel_hi:[1,0]
	v_pk_mul_f32 v[14:15], v[14:15], v[234:235] op_sel_hi:[1,0]
	v_pk_mul_f32 v[16:17], v[16:17], v[234:235] op_sel_hi:[1,0]
	v_pk_mul_f32 v[10:11], v[10:11], v[234:235] op_sel_hi:[1,0]
	v_pk_mul_f32 v[12:13], v[12:13], v[234:235] op_sel_hi:[1,0]
	v_cmp_lt_i32_e32 vcc, 13, v1
	s_and_saveexec_b64 s[46:47], vcc
	s_cbranch_execz .Lffin_pub_done
	v_add_u32_e32 v167, -14, v1
	v_lshlrev_b32_e32 v171, 7, v167
	v_lshl_add_u32 v171, v163, 2, v171
	v_add_u32_e32 v171, s63, v171
	ds_write_b128 v171, v[78:81]
	ds_write_b128 v171, v[74:77] offset:16
	ds_write_b128 v171, v[14:17] offset:256
	ds_write_b128 v171, v[10:13] offset:272
	s_and_b64 vcc, exec, s[4:5]
	s_cbranch_vccz .Lffin_pub_done
	s_lshl_b32 s44, s42, 1
	v_add_u32_e32 v167, s44, v167
	s_movk_i32 s3, 0x2c00
	v_mov_b64_e32 v[222:223], s[16:17]
	v_mad_u64_u32 v[222:223], s[44:45], v167, s3, v[222:223]
	v_lshlrev_b32_e32 v167, 2, v169
	s_nop 0
	v_add_co_u32_e32 v222, vcc, v222, v167
	s_nop 1
	v_addc_co_u32_e32 v223, vcc, 0, v223, vcc
	global_store_dwordx4 v[222:223], v[14:17], off
	global_store_dwordx4 v[222:223], v[10:13], off offset:16
.Lffin_pub_done:
	s_or_b64 exec, exec, s[46:47]
	s_waitcnt lgkmcnt(0)
	s_barrier
	v_pk_mul_f32 v[158:159], v[158:159], v[162:163] op_sel_hi:[1,0]
	v_pk_mul_f32 v[160:161], v[160:161], v[162:163] op_sel_hi:[1,0]
	v_pk_mul_f32 v[154:155], v[154:155], v[162:163] op_sel_hi:[1,0]
	v_pk_mul_f32 v[156:157], v[156:157], v[162:163] op_sel_hi:[1,0]
	s_and_b64 vcc, exec, s[4:5]
	s_cbranch_vccz .Lffin_nofix_a
	v_lshl_add_u32 v167, v163, 2, s62
	ds_read_b128 v[192:195], v167
	ds_read_b128 v[196:199], v167 offset:16
	ds_read_b128 v[200:203], v167 offset:128
	ds_read_b128 v[204:207], v167 offset:144
.Lffin_nofix_a:
	v_pk_fma_f32 v[236:237], v[122:123], v[158:159], v[130:131]
	v_pk_fma_f32 v[238:239], v[124:125], v[160:161], v[132:133]
	v_pk_fma_f32 v[240:241], v[126:127], v[154:155], v[134:135]
	v_pk_fma_f32 v[242:243], v[128:129], v[156:157], v[136:137]
	v_pk_mul_f32 v[150:151], v[150:151], v[162:163] op_sel_hi:[1,0]
	v_pk_mul_f32 v[152:153], v[152:153], v[162:163] op_sel_hi:[1,0]
	v_pk_mul_f32 v[146:147], v[146:147], v[162:163] op_sel_hi:[1,0]
	v_pk_mul_f32 v[148:149], v[148:149], v[162:163] op_sel_hi:[1,0]
	v_fmac_f32_dpp v236, v158, v114 row_shr:1 row_mask:0xf bank_mask:0xf bound_ctrl:1
	v_fmac_f32_dpp v237, v159, v115 row_shr:1 row_mask:0xf bank_mask:0xf bound_ctrl:1
	v_fmac_f32_dpp v238, v160, v116 row_shr:1 row_mask:0xf bank_mask:0xf bound_ctrl:1
	v_fmac_f32_dpp v239, v161, v117 row_shr:1 row_mask:0xf bank_mask:0xf bound_ctrl:1
	v_fmac_f32_dpp v240, v154, v118 row_shr:1 row_mask:0xf bank_mask:0xf bound_ctrl:1
	v_fmac_f32_dpp v241, v155, v119 row_shr:1 row_mask:0xf bank_mask:0xf bound_ctrl:1
	v_fmac_f32_dpp v242, v156, v120 row_shr:1 row_mask:0xf bank_mask:0xf bound_ctrl:1
	v_fmac_f32_dpp v243, v157, v121 row_shr:1 row_mask:0xf bank_mask:0xf bound_ctrl:1
	v_fmac_f32_dpp v236, v158, v106 row_shr:2 row_mask:0xf bank_mask:0xf bound_ctrl:1
	v_fmac_f32_dpp v237, v159, v107 row_shr:2 row_mask:0xf bank_mask:0xf bound_ctrl:1
	v_fmac_f32_dpp v238, v160, v108 row_shr:2 row_mask:0xf bank_mask:0xf bound_ctrl:1
	v_fmac_f32_dpp v239, v161, v109 row_shr:2 row_mask:0xf bank_mask:0xf bound_ctrl:1
	v_fmac_f32_dpp v240, v154, v110 row_shr:2 row_mask:0xf bank_mask:0xf bound_ctrl:1
	v_fmac_f32_dpp v241, v155, v111 row_shr:2 row_mask:0xf bank_mask:0xf bound_ctrl:1
	v_fmac_f32_dpp v242, v156, v112 row_shr:2 row_mask:0xf bank_mask:0xf bound_ctrl:1
	v_fmac_f32_dpp v243, v157, v113 row_shr:2 row_mask:0xf bank_mask:0xf bound_ctrl:1
	s_and_b64 vcc, exec, s[4:5]
	s_cbranch_vccz .Lffin_nofix_b
	v_cmp_eq_u32_e64 s[44:45], 0, v1
	v_cmp_eq_u32_e64 s[46:47], 1, v1
	s_waitcnt lgkmcnt(0)
	s_mov_b64 exec, s[44:45]
	v_pk_fma_f32 v[236:237], v[114:115], v[200:201], v[236:237]
	v_pk_fma_f32 v[238:239], v[116:117], v[202:203], v[238:239]
	v_pk_fma_f32 v[240:241], v[118:119], v[204:205], v[240:241]
	v_pk_fma_f32 v[242:243], v[120:121], v[206:207], v[242:243]
	v_pk_fma_f32 v[236:237], v[106:107], v[192:193], v[236:237]
	v_pk_fma_f32 v[238:239], v[108:109], v[194:195], v[238:239]
	v_pk_fma_f32 v[240:241], v[110:111], v[196:197], v[240:241]
	v_pk_fma_f32 v[242:243], v[112:113], v[198:199], v[242:243]
	s_mov_b64 exec, s[46:47]
	v_pk_fma_f32 v[236:237], v[106:107], v[200:201], v[236:237]
	v_pk_fma_f32 v[238:239], v[108:109], v[202:203], v[238:239]
	v_pk_fma_f32 v[240:241], v[110:111], v[204:205], v[240:241]
	v_pk_fma_f32 v[242:243], v[112:113], v[206:207], v[242:243]
	s_mov_b64 exec, -1
;     __device__ __forceinline__ void operator()(const f32x4 (&acc)[2][2][4][2], const Unit& u, int wr, int wc, int fr, int fq) const {
;     ...
;             for (int m = 0; m < 4; ++m) {
;                 const int row = row0 + ai * HALF + m * 16; const float rs = rsv[m];
;                 const f32x4 ca = acc[ai][0][m][0] * rs, cb_ = acc[ai][0][m][1] * rs;
;                 f32x4 aa = w2a * ca + ba, ab = w2b * cb_ + bb;
; #pragma unroll
;                 for (int c = 0; c < 4; ++c) { aa[c] = __builtin_fmaf(w1a[c], dpp_shr1(ca[c]), aa[c]); ab[c] = __builtin_fmaf(w1b[c], dpp_shr1(cb_[c]), ab[c]);
;                     aa[c] = __builtin_fmaf(w0a[c], dpp_shr2(ca[c]), aa[c]); ab[c] = __builtin_fmaf(w0b[c], dpp_shr2(cb_[c]), ab[c]); }
;                 if (m == 0) {
;                     if (ai == 1 || wr == 1) { const int sw = ((ai == 1 && wr == 0) ? 4 : 0) + wc, sai = (ai == 1 && wr == 1) ? 1 : 0;
;                         const PG8_LAS f32x4* xp = (const PG8_LAS f32x4*)(X + ((sw * 2 + sai) * 2) * 32 + fq * 8); const f32x4 h0a = xp[0], h0b = xp[1], h1a = xp[8], h1b = xp[9];
;                         aa += w1a * (h1a * m0) + w0a * (h0a * m0 + h1a * m1); ab += w1b * (h1b * m0) + w0b * (h0b * m0 + h1b * m1); }
;                 } else {
; #pragma unroll
;                     for (int c = 0; c < 4; ++c) { aa[c] = __builtin_fmaf(w1a[c], dpp_shl15(pa[c]), aa[c]); ab[c] = __builtin_fmaf(w1b[c], dpp_shl15(pb[c]), ab[c]);
;                         aa[c] = __builtin_fmaf(w0a[c], dpp_shl14(pa[c]), aa[c]); ab[c] = __builtin_fmaf(w0b[c], dpp_shl14(pb[c]), ab[c]); }
;                 }
;                 const f32x4 ga = acc[ai][1][m][0] * rs, gb = acc[ai][1][m][1] * rs;
;                 f32x4 ea = aa * -1.4426950408889634f, eb = ab * -1.4426950408889634f;
; #pragma unroll
;                 for (int c = 0; c < 4; ++c) { ea[c] = __builtin_amdgcn_exp2f(ea[c]); eb[c] = __builtin_amdgcn_exp2f(eb[c]); }
;                 ea = ea + 1.0f; eb = eb + 1.0f;
; #pragma unroll
;                 for (int c = 0; c < 4; ++c) { ea[c] = __builtin_amdgcn_rcpf(ea[c]); eb[c] = __builtin_amdgcn_rcpf(eb[c]); }
;                 const f32x4 oa = (aa * ga) * ea, ob = (ab * gb) * eb;
;                 u32x4 w; w.x = cvt_pk_bf16(oa[0], oa[1]); w.y = cvt_pk_bf16(oa[2], oa[3]); w.z = cvt_pk_bf16(ob[0], ob[1]); w.w = cvt_pk_bf16(ob[2], ob[3]);
;                 *(u32x4*)(act + (size_t)row * FF + col) = w;
.Lffin_nofix_b:
	s_and_b32 s44, s42, 15
	s_cmp_lg_u32 s44, 0
	s_cselect_b64 s[44:45], -1, 0
	s_and_b64 s[44:45], s[44:45], s[30:31]
	v_cmp_gt_i32_e32 vcc, 2, v1
	s_and_b64 s[44:45], s[44:45], vcc
	s_and_saveexec_b64 s[46:47], s[44:45]
	s_cbranch_execz .Lffin_nopark
	s_lshl_b32 s44, s42, 1
	v_add_u32_e32 v167, s44, v1
	s_movk_i32 s3, 0x2c00
	v_mov_b64_e32 v[222:223], s[20:21]
	v_mov_b64_e32 v[208:209], s[22:23]
	v_mad_u64_u32 v[222:223], s[44:45], v167, s3, v[222:223]
	v_mad_u64_u32 v[208:209], s[44:45], v167, s3, v[208:209]
	v_lshlrev_b32_e32 v167, 2, v169
	s_nop 0
	v_add_co_u32_e32 v222, vcc, v222, v167
	s_nop 1
	v_addc_co_u32_e32 v223, vcc, 0, v223, vcc
	v_add_co_u32_e32 v208, vcc, v208, v167
	s_nop 1
	v_addc_co_u32_e32 v209, vcc, 0, v209, vcc
	global_store_dwordx4 v[222:223], v[236:239], off
	global_store_dwordx4 v[222:223], v[240:243], off offset:16
	global_store_dwordx4 v[208:209], v[150:153], off
	global_store_dwordx4 v[208:209], v[146:149], off offset:16
.Lffin_nopark:
	s_or_b64 exec, exec, s[46:47]
	v_pk_mul_f32 v[244:245], v[236:237], s[92:93] op_sel_hi:[1,0]
	v_pk_mul_f32 v[246:247], v[238:239], s[92:93] op_sel_hi:[1,0]
	v_pk_mul_f32 v[248:249], v[240:241], s[92:93] op_sel_hi:[1,0]
	v_pk_mul_f32 v[250:251], v[242:243], s[92:93] op_sel_hi:[1,0]
	v_exp_f32_e32 v244, v244
	v_exp_f32_e32 v245, v245
	v_exp_f32_e32 v246, v246
	v_exp_f32_e32 v247, v247
	v_exp_f32_e32 v248, v248
	v_exp_f32_e32 v249, v249
	v_exp_f32_e32 v250, v250
	v_exp_f32_e32 v251, v251
	v_pk_mul_f32 v[236:237], v[236:237], v[150:151]
	v_pk_mul_f32 v[238:239], v[238:239], v[152:153]
	v_pk_mul_f32 v[240:241], v[240:241], v[146:147]
	v_pk_mul_f32 v[242:243], v[242:243], v[148:149]
	v_pk_add_f32 v[244:245], v[244:245], 1.0 op_sel_hi:[1,0]
	v_pk_add_f32 v[246:247], v[246:247], 1.0 op_sel_hi:[1,0]
	v_pk_add_f32 v[248:249], v[248:249], 1.0 op_sel_hi:[1,0]
	v_pk_add_f32 v[250:251], v[250:251], 1.0 op_sel_hi:[1,0]
	v_rcp_f32_e32 v244, v244
	v_rcp_f32_e32 v245, v245
	v_rcp_f32_e32 v246, v246
	v_rcp_f32_e32 v247, v247
	v_rcp_f32_e32 v248, v248
	v_rcp_f32_e32 v249, v249
	v_rcp_f32_e32 v250, v250
	v_rcp_f32_e32 v251, v251
	s_nop 0
	v_pk_mul_f32 v[236:237], v[236:237], v[244:245]
	v_pk_mul_f32 v[238:239], v[238:239], v[246:247]
	v_pk_mul_f32 v[240:241], v[240:241], v[248:249]
	v_pk_mul_f32 v[242:243], v[242:243], v[250:251]
	v_cvt_pk_bf16_f32 v216, v236, v237
	v_cvt_pk_bf16_f32 v217, v238, v239
	v_cvt_pk_bf16_f32 v218, v240, v241
	v_cvt_pk_bf16_f32 v219, v242, v243
	global_store_dwordx4 v[220:221], v[216:219], off
	v_lshl_add_u64 v[220:221], v[220:221], 0, s[100:101]
	v_pk_mul_f32 v[142:143], v[142:143], v[164:165] op_sel_hi:[1,0]
	v_pk_mul_f32 v[144:145], v[144:145], v[164:165] op_sel_hi:[1,0]
	v_pk_mul_f32 v[138:139], v[138:139], v[164:165] op_sel_hi:[1,0]
	v_pk_mul_f32 v[140:141], v[140:141], v[164:165] op_sel_hi:[1,0]
	v_pk_fma_f32 v[236:237], v[122:123], v[142:143], v[130:131]
	v_pk_fma_f32 v[238:239], v[124:125], v[144:145], v[132:133]
	v_pk_fma_f32 v[240:241], v[126:127], v[138:139], v[134:135]
	v_pk_fma_f32 v[242:243], v[128:129], v[140:141], v[136:137]
	v_pk_mul_f32 v[102:103], v[102:103], v[164:165] op_sel_hi:[1,0]
	v_pk_mul_f32 v[104:105], v[104:105], v[164:165] op_sel_hi:[1,0]
	v_pk_mul_f32 v[98:99], v[98:99], v[164:165] op_sel_hi:[1,0]
	v_pk_mul_f32 v[100:101], v[100:101], v[164:165] op_sel_hi:[1,0]
	v_fmac_f32_dpp v236, v142, v114 row_shr:1 row_mask:0xf bank_mask:0xf bound_ctrl:1
	v_fmac_f32_dpp v237, v143, v115 row_shr:1 row_mask:0xf bank_mask:0xf bound_ctrl:1
	v_fmac_f32_dpp v238, v144, v116 row_shr:1 row_mask:0xf bank_mask:0xf bound_ctrl:1
	v_fmac_f32_dpp v239, v145, v117 row_shr:1 row_mask:0xf bank_mask:0xf bound_ctrl:1
	v_fmac_f32_dpp v240, v138, v118 row_shr:1 row_mask:0xf bank_mask:0xf bound_ctrl:1
	v_fmac_f32_dpp v241, v139, v119 row_shr:1 row_mask:0xf bank_mask:0xf bound_ctrl:1
	v_fmac_f32_dpp v242, v140, v120 row_shr:1 row_mask:0xf bank_mask:0xf bound_ctrl:1
	v_fmac_f32_dpp v243, v141, v121 row_shr:1 row_mask:0xf bank_mask:0xf bound_ctrl:1
	v_fmac_f32_dpp v236, v142, v106 row_shr:2 row_mask:0xf bank_mask:0xf bound_ctrl:1
	v_fmac_f32_dpp v237, v143, v107 row_shr:2 row_mask:0xf bank_mask:0xf bound_ctrl:1
	v_fmac_f32_dpp v238, v144, v108 row_shr:2 row_mask:0xf bank_mask:0xf bound_ctrl:1
	v_fmac_f32_dpp v239, v145, v109 row_shr:2 row_mask:0xf bank_mask:0xf bound_ctrl:1
	v_fmac_f32_dpp v240, v138, v110 row_shr:2 row_mask:0xf bank_mask:0xf bound_ctrl:1
	v_fmac_f32_dpp v241, v139, v111 row_shr:2 row_mask:0xf bank_mask:0xf bound_ctrl:1
	v_fmac_f32_dpp v242, v140, v112 row_shr:2 row_mask:0xf bank_mask:0xf bound_ctrl:1
	v_fmac_f32_dpp v243, v141, v113 row_shr:2 row_mask:0xf bank_mask:0xf bound_ctrl:1
	v_fmac_f32_dpp v236, v158, v114 row_shl:15 row_mask:0xf bank_mask:0xf bound_ctrl:1
	v_fmac_f32_dpp v237, v159, v115 row_shl:15 row_mask:0xf bank_mask:0xf bound_ctrl:1
	v_fmac_f32_dpp v238, v160, v116 row_shl:15 row_mask:0xf bank_mask:0xf bound_ctrl:1
	v_fmac_f32_dpp v239, v161, v117 row_shl:15 row_mask:0xf bank_mask:0xf bound_ctrl:1
	v_fmac_f32_dpp v240, v154, v118 row_shl:15 row_mask:0xf bank_mask:0xf bound_ctrl:1
	v_fmac_f32_dpp v241, v155, v119 row_shl:15 row_mask:0xf bank_mask:0xf bound_ctrl:1
	v_fmac_f32_dpp v242, v156, v120 row_shl:15 row_mask:0xf bank_mask:0xf bound_ctrl:1
	v_fmac_f32_dpp v243, v157, v121 row_shl:15 row_mask:0xf bank_mask:0xf bound_ctrl:1
	v_fmac_f32_dpp v236, v158, v106 row_shl:14 row_mask:0xf bank_mask:0xf bound_ctrl:1
	v_fmac_f32_dpp v237, v159, v107 row_shl:14 row_mask:0xf bank_mask:0xf bound_ctrl:1
	v_fmac_f32_dpp v238, v160, v108 row_shl:14 row_mask:0xf bank_mask:0xf bound_ctrl:1
	v_fmac_f32_dpp v239, v161, v109 row_shl:14 row_mask:0xf bank_mask:0xf bound_ctrl:1
;     __device__ __forceinline__ void operator()(const f32x4 (&acc)[2][2][4][2], const Unit& u, int wr, int wc, int fr, int fq) const {
;     ...
;             for (int m = 0; m < 4; ++m) {
;                 const int row = row0 + ai * HALF + m * 16; const float rs = rsv[m];
;                 const f32x4 ca = acc[ai][0][m][0] * rs, cb_ = acc[ai][0][m][1] * rs;
;                 f32x4 aa = w2a * ca + ba, ab = w2b * cb_ + bb;
; #pragma unroll
;                 for (int c = 0; c < 4; ++c) { aa[c] = __builtin_fmaf(w1a[c], dpp_shr1(ca[c]), aa[c]); ab[c] = __builtin_fmaf(w1b[c], dpp_shr1(cb_[c]), ab[c]);
;                     aa[c] = __builtin_fmaf(w0a[c], dpp_shr2(ca[c]), aa[c]); ab[c] = __builtin_fmaf(w0b[c], dpp_shr2(cb_[c]), ab[c]); }
;                 if (m == 0) {
;                     if (ai == 1 || wr == 1) { const int sw = ((ai == 1 && wr == 0) ? 4 : 0) + wc, sai = (ai == 1 && wr == 1) ? 1 : 0;
;                         const PG8_LAS f32x4* xp = (const PG8_LAS f32x4*)(X + ((sw * 2 + sai) * 2) * 32 + fq * 8); const f32x4 h0a = xp[0], h0b = xp[1], h1a = xp[8], h1b = xp[9];
;                         aa += w1a * (h1a * m0) + w0a * (h0a * m0 + h1a * m1); ab += w1b * (h1b * m0) + w0b * (h0b * m0 + h1b * m1); }
;                 } else {
; #pragma unroll
;                     for (int c = 0; c < 4; ++c) { aa[c] = __builtin_fmaf(w1a[c], dpp_shl15(pa[c]), aa[c]); ab[c] = __builtin_fmaf(w1b[c], dpp_shl15(pb[c]), ab[c]);
;                         aa[c] = __builtin_fmaf(w0a[c], dpp_shl14(pa[c]), aa[c]); ab[c] = __builtin_fmaf(w0b[c], dpp_shl14(pb[c]), ab[c]); }
;                 }
;                 const f32x4 ga = acc[ai][1][m][0] * rs, gb = acc[ai][1][m][1] * rs;
;                 f32x4 ea = aa * -1.4426950408889634f, eb = ab * -1.4426950408889634f;
; #pragma unroll
;                 for (int c = 0; c < 4; ++c) { ea[c] = __builtin_amdgcn_exp2f(ea[c]); eb[c] = __builtin_amdgcn_exp2f(eb[c]); }
;                 ea = ea + 1.0f; eb = eb + 1.0f;
; #pragma unroll
;                 for (int c = 0; c < 4; ++c) { ea[c] = __builtin_amdgcn_rcpf(ea[c]); eb[c] = __builtin_amdgcn_rcpf(eb[c]); }
;                 const f32x4 oa = (aa * ga) * ea, ob = (ab * gb) * eb;
;                 u32x4 w; w.x = cvt_pk_bf16(oa[0], oa[1]); w.y = cvt_pk_bf16(oa[2], oa[3]); w.z = cvt_pk_bf16(ob[0], ob[1]); w.w = cvt_pk_bf16(ob[2], ob[3]);
;                 *(u32x4*)(act + (size_t)row * FF + col) = w;
	v_fmac_f32_dpp v240, v154, v110 row_shl:14 row_mask:0xf bank_mask:0xf bound_ctrl:1
	v_fmac_f32_dpp v241, v155, v111 row_shl:14 row_mask:0xf bank_mask:0xf bound_ctrl:1
	v_fmac_f32_dpp v242, v156, v112 row_shl:14 row_mask:0xf bank_mask:0xf bound_ctrl:1
	v_fmac_f32_dpp v243, v157, v113 row_shl:14 row_mask:0xf bank_mask:0xf bound_ctrl:1
	v_pk_mul_f32 v[244:245], v[236:237], s[92:93] op_sel_hi:[1,0]
	v_pk_mul_f32 v[246:247], v[238:239], s[92:93] op_sel_hi:[1,0]
	v_pk_mul_f32 v[248:249], v[240:241], s[92:93] op_sel_hi:[1,0]
	v_pk_mul_f32 v[250:251], v[242:243], s[92:93] op_sel_hi:[1,0]
	v_exp_f32_e32 v244, v244
	v_exp_f32_e32 v245, v245
	v_exp_f32_e32 v246, v246
	v_exp_f32_e32 v247, v247
	v_exp_f32_e32 v248, v248
	v_exp_f32_e32 v249, v249
	v_exp_f32_e32 v250, v250
	v_exp_f32_e32 v251, v251
	v_pk_mul_f32 v[236:237], v[236:237], v[102:103]
	v_pk_mul_f32 v[238:239], v[238:239], v[104:105]
	v_pk_mul_f32 v[240:241], v[240:241], v[98:99]
	v_pk_mul_f32 v[242:243], v[242:243], v[100:101]
	v_pk_add_f32 v[244:245], v[244:245], 1.0 op_sel_hi:[1,0]
	v_pk_add_f32 v[246:247], v[246:247], 1.0 op_sel_hi:[1,0]
	v_pk_add_f32 v[248:249], v[248:249], 1.0 op_sel_hi:[1,0]
	v_pk_add_f32 v[250:251], v[250:251], 1.0 op_sel_hi:[1,0]
	v_rcp_f32_e32 v244, v244
	v_rcp_f32_e32 v245, v245
	v_rcp_f32_e32 v246, v246
	v_rcp_f32_e32 v247, v247
	v_rcp_f32_e32 v248, v248
	v_rcp_f32_e32 v249, v249
	v_rcp_f32_e32 v250, v250
	v_rcp_f32_e32 v251, v251
	s_nop 0
	v_pk_mul_f32 v[236:237], v[236:237], v[244:245]
	v_pk_mul_f32 v[238:239], v[238:239], v[246:247]
	v_pk_mul_f32 v[240:241], v[240:241], v[248:249]
	v_pk_mul_f32 v[242:243], v[242:243], v[250:251]
	v_cvt_pk_bf16_f32 v216, v236, v237
	v_cvt_pk_bf16_f32 v217, v238, v239
	v_cvt_pk_bf16_f32 v218, v240, v241
	v_cvt_pk_bf16_f32 v219, v242, v243
	global_store_dwordx4 v[220:221], v[216:219], off
	v_lshl_add_u64 v[220:221], v[220:221], 0, s[100:101]
	v_pk_mul_f32 v[94:95], v[94:95], v[166:167] op_sel_hi:[1,0]
	v_pk_mul_f32 v[96:97], v[96:97], v[166:167] op_sel_hi:[1,0]
	v_pk_mul_f32 v[90:91], v[90:91], v[166:167] op_sel_hi:[1,0]
	v_pk_mul_f32 v[92:93], v[92:93], v[166:167] op_sel_hi:[1,0]
	v_pk_fma_f32 v[236:237], v[122:123], v[94:95], v[130:131]
	v_pk_fma_f32 v[238:239], v[124:125], v[96:97], v[132:133]
	v_pk_fma_f32 v[240:241], v[126:127], v[90:91], v[134:135]
	v_pk_fma_f32 v[242:243], v[128:129], v[92:93], v[136:137]
	v_pk_mul_f32 v[86:87], v[86:87], v[166:167] op_sel_hi:[1,0]
	v_pk_mul_f32 v[88:89], v[88:89], v[166:167] op_sel_hi:[1,0]
	v_pk_mul_f32 v[82:83], v[82:83], v[166:167] op_sel_hi:[1,0]
	v_pk_mul_f32 v[84:85], v[84:85], v[166:167] op_sel_hi:[1,0]
	v_fmac_f32_dpp v236, v94, v114 row_shr:1 row_mask:0xf bank_mask:0xf bound_ctrl:1
	v_fmac_f32_dpp v237, v95, v115 row_shr:1 row_mask:0xf bank_mask:0xf bound_ctrl:1
	v_fmac_f32_dpp v238, v96, v116 row_shr:1 row_mask:0xf bank_mask:0xf bound_ctrl:1
	v_fmac_f32_dpp v239, v97, v117 row_shr:1 row_mask:0xf bank_mask:0xf bound_ctrl:1
	v_fmac_f32_dpp v240, v90, v118 row_shr:1 row_mask:0xf bank_mask:0xf bound_ctrl:1
	v_fmac_f32_dpp v241, v91, v119 row_shr:1 row_mask:0xf bank_mask:0xf bound_ctrl:1
	v_fmac_f32_dpp v242, v92, v120 row_shr:1 row_mask:0xf bank_mask:0xf bound_ctrl:1
	v_fmac_f32_dpp v243, v93, v121 row_shr:1 row_mask:0xf bank_mask:0xf bound_ctrl:1
	v_fmac_f32_dpp v236, v94, v106 row_shr:2 row_mask:0xf bank_mask:0xf bound_ctrl:1
	v_fmac_f32_dpp v237, v95, v107 row_shr:2 row_mask:0xf bank_mask:0xf bound_ctrl:1
	v_fmac_f32_dpp v238, v96, v108 row_shr:2 row_mask:0xf bank_mask:0xf bound_ctrl:1
	v_fmac_f32_dpp v239, v97, v109 row_shr:2 row_mask:0xf bank_mask:0xf bound_ctrl:1
	v_fmac_f32_dpp v240, v90, v110 row_shr:2 row_mask:0xf bank_mask:0xf bound_ctrl:1
	v_fmac_f32_dpp v241, v91, v111 row_shr:2 row_mask:0xf bank_mask:0xf bound_ctrl:1
	v_fmac_f32_dpp v242, v92, v112 row_shr:2 row_mask:0xf bank_mask:0xf bound_ctrl:1
	v_fmac_f32_dpp v243, v93, v113 row_shr:2 row_mask:0xf bank_mask:0xf bound_ctrl:1
	v_fmac_f32_dpp v236, v142, v114 row_shl:15 row_mask:0xf bank_mask:0xf bound_ctrl:1
	v_fmac_f32_dpp v237, v143, v115 row_shl:15 row_mask:0xf bank_mask:0xf bound_ctrl:1
	v_fmac_f32_dpp v238, v144, v116 row_shl:15 row_mask:0xf bank_mask:0xf bound_ctrl:1
	v_fmac_f32_dpp v239, v145, v117 row_shl:15 row_mask:0xf bank_mask:0xf bound_ctrl:1
	v_fmac_f32_dpp v240, v138, v118 row_shl:15 row_mask:0xf bank_mask:0xf bound_ctrl:1
	v_fmac_f32_dpp v241, v139, v119 row_shl:15 row_mask:0xf bank_mask:0xf bound_ctrl:1
	v_fmac_f32_dpp v242, v140, v120 row_shl:15 row_mask:0xf bank_mask:0xf bound_ctrl:1
	v_fmac_f32_dpp v243, v141, v121 row_shl:15 row_mask:0xf bank_mask:0xf bound_ctrl:1
	v_fmac_f32_dpp v236, v142, v106 row_shl:14 row_mask:0xf bank_mask:0xf bound_ctrl:1
	v_fmac_f32_dpp v237, v143, v107 row_shl:14 row_mask:0xf bank_mask:0xf bound_ctrl:1
	v_fmac_f32_dpp v238, v144, v108 row_shl:14 row_mask:0xf bank_mask:0xf bound_ctrl:1
	v_fmac_f32_dpp v239, v145, v109 row_shl:14 row_mask:0xf bank_mask:0xf bound_ctrl:1
	v_fmac_f32_dpp v240, v138, v110 row_shl:14 row_mask:0xf bank_mask:0xf bound_ctrl:1
	v_fmac_f32_dpp v241, v139, v111 row_shl:14 row_mask:0xf bank_mask:0xf bound_ctrl:1
	v_fmac_f32_dpp v242, v140, v112 row_shl:14 row_mask:0xf bank_mask:0xf bound_ctrl:1
	v_fmac_f32_dpp v243, v141, v113 row_shl:14 row_mask:0xf bank_mask:0xf bound_ctrl:1
	v_pk_mul_f32 v[244:245], v[236:237], s[92:93] op_sel_hi:[1,0]
	v_pk_mul_f32 v[246:247], v[238:239], s[92:93] op_sel_hi:[1,0]
	v_pk_mul_f32 v[248:249], v[240:241], s[92:93] op_sel_hi:[1,0]
	v_pk_mul_f32 v[250:251], v[242:243], s[92:93] op_sel_hi:[1,0]
	v_exp_f32_e32 v244, v244
	v_exp_f32_e32 v245, v245
	v_exp_f32_e32 v246, v246
	v_exp_f32_e32 v247, v247
	v_exp_f32_e32 v248, v248
;     __device__ __forceinline__ void operator()(const f32x4 (&acc)[2][2][4][2], const Unit& u, int wr, int wc, int fr, int fq) const {
;     ...
;             for (int m = 0; m < 4; ++m) {
;                 const int row = row0 + ai * HALF + m * 16; const float rs = rsv[m];
;                 const f32x4 ca = acc[ai][0][m][0] * rs, cb_ = acc[ai][0][m][1] * rs;
;                 f32x4 aa = w2a * ca + ba, ab = w2b * cb_ + bb;
; #pragma unroll
;                 for (int c = 0; c < 4; ++c) { aa[c] = __builtin_fmaf(w1a[c], dpp_shr1(ca[c]), aa[c]); ab[c] = __builtin_fmaf(w1b[c], dpp_shr1(cb_[c]), ab[c]);
;                     aa[c] = __builtin_fmaf(w0a[c], dpp_shr2(ca[c]), aa[c]); ab[c] = __builtin_fmaf(w0b[c], dpp_shr2(cb_[c]), ab[c]); }
;                 if (m == 0) {
;                     if (ai == 1 || wr == 1) { const int sw = ((ai == 1 && wr == 0) ? 4 : 0) + wc, sai = (ai == 1 && wr == 1) ? 1 : 0;
;                         const PG8_LAS f32x4* xp = (const PG8_LAS f32x4*)(X + ((sw * 2 + sai) * 2) * 32 + fq * 8); const f32x4 h0a = xp[0], h0b = xp[1], h1a = xp[8], h1b = xp[9];
;                         aa += w1a * (h1a * m0) + w0a * (h0a * m0 + h1a * m1); ab += w1b * (h1b * m0) + w0b * (h0b * m0 + h1b * m1); }
;                 } else {
; #pragma unroll
;                     for (int c = 0; c < 4; ++c) { aa[c] = __builtin_fmaf(w1a[c], dpp_shl15(pa[c]), aa[c]); ab[c] = __builtin_fmaf(w1b[c], dpp_shl15(pb[c]), ab[c]);
;                         aa[c] = __builtin_fmaf(w0a[c], dpp_shl14(pa[c]), aa[c]); ab[c] = __builtin_fmaf(w0b[c], dpp_shl14(pb[c]), ab[c]); }
;                 }
;                 const f32x4 ga = acc[ai][1][m][0] * rs, gb = acc[ai][1][m][1] * rs;
;                 f32x4 ea = aa * -1.4426950408889634f, eb = ab * -1.4426950408889634f;
; #pragma unroll
;                 for (int c = 0; c < 4; ++c) { ea[c] = __builtin_amdgcn_exp2f(ea[c]); eb[c] = __builtin_amdgcn_exp2f(eb[c]); }
;                 ea = ea + 1.0f; eb = eb + 1.0f;
; #pragma unroll
;                 for (int c = 0; c < 4; ++c) { ea[c] = __builtin_amdgcn_rcpf(ea[c]); eb[c] = __builtin_amdgcn_rcpf(eb[c]); }
;                 const f32x4 oa = (aa * ga) * ea, ob = (ab * gb) * eb;
;                 u32x4 w; w.x = cvt_pk_bf16(oa[0], oa[1]); w.y = cvt_pk_bf16(oa[2], oa[3]); w.z = cvt_pk_bf16(ob[0], ob[1]); w.w = cvt_pk_bf16(ob[2], ob[3]);
;                 *(u32x4*)(act + (size_t)row * FF + col) = w;
	v_exp_f32_e32 v249, v249
	v_exp_f32_e32 v250, v250
	v_exp_f32_e32 v251, v251
	v_pk_mul_f32 v[236:237], v[236:237], v[86:87]
	v_pk_mul_f32 v[238:239], v[238:239], v[88:89]
	v_pk_mul_f32 v[240:241], v[240:241], v[82:83]
	v_pk_mul_f32 v[242:243], v[242:243], v[84:85]
	v_pk_add_f32 v[244:245], v[244:245], 1.0 op_sel_hi:[1,0]
	v_pk_add_f32 v[246:247], v[246:247], 1.0 op_sel_hi:[1,0]
	v_pk_add_f32 v[248:249], v[248:249], 1.0 op_sel_hi:[1,0]
	v_pk_add_f32 v[250:251], v[250:251], 1.0 op_sel_hi:[1,0]
	v_rcp_f32_e32 v244, v244
	v_rcp_f32_e32 v245, v245
	v_rcp_f32_e32 v246, v246
	v_rcp_f32_e32 v247, v247
	v_rcp_f32_e32 v248, v248
	v_rcp_f32_e32 v249, v249
	v_rcp_f32_e32 v250, v250
	v_rcp_f32_e32 v251, v251
	s_nop 0
	v_pk_mul_f32 v[236:237], v[236:237], v[244:245]
	v_pk_mul_f32 v[238:239], v[238:239], v[246:247]
	v_pk_mul_f32 v[240:241], v[240:241], v[248:249]
	v_pk_mul_f32 v[242:243], v[242:243], v[250:251]
	v_cvt_pk_bf16_f32 v216, v236, v237
	v_cvt_pk_bf16_f32 v217, v238, v239
	v_cvt_pk_bf16_f32 v218, v240, v241
	v_cvt_pk_bf16_f32 v219, v242, v243
	global_store_dwordx4 v[220:221], v[216:219], off
	v_lshl_add_u64 v[220:221], v[220:221], 0, s[100:101]
	v_pk_fma_f32 v[236:237], v[122:123], v[78:79], v[130:131]
	v_pk_fma_f32 v[238:239], v[124:125], v[80:81], v[132:133]
	v_pk_fma_f32 v[240:241], v[126:127], v[74:75], v[134:135]
	v_pk_fma_f32 v[242:243], v[128:129], v[76:77], v[136:137]
	v_pk_mul_f32 v[70:71], v[70:71], v[168:169] op_sel_hi:[1,0]
	v_pk_mul_f32 v[72:73], v[72:73], v[168:169] op_sel_hi:[1,0]
	v_pk_mul_f32 v[66:67], v[66:67], v[168:169] op_sel_hi:[1,0]
	v_pk_mul_f32 v[68:69], v[68:69], v[168:169] op_sel_hi:[1,0]
	v_fmac_f32_dpp v236, v78, v114 row_shr:1 row_mask:0xf bank_mask:0xf bound_ctrl:1
	v_fmac_f32_dpp v237, v79, v115 row_shr:1 row_mask:0xf bank_mask:0xf bound_ctrl:1
	v_fmac_f32_dpp v238, v80, v116 row_shr:1 row_mask:0xf bank_mask:0xf bound_ctrl:1
	v_fmac_f32_dpp v239, v81, v117 row_shr:1 row_mask:0xf bank_mask:0xf bound_ctrl:1
	v_fmac_f32_dpp v240, v74, v118 row_shr:1 row_mask:0xf bank_mask:0xf bound_ctrl:1
	v_fmac_f32_dpp v241, v75, v119 row_shr:1 row_mask:0xf bank_mask:0xf bound_ctrl:1
	v_fmac_f32_dpp v242, v76, v120 row_shr:1 row_mask:0xf bank_mask:0xf bound_ctrl:1
	v_fmac_f32_dpp v243, v77, v121 row_shr:1 row_mask:0xf bank_mask:0xf bound_ctrl:1
	v_fmac_f32_dpp v236, v78, v106 row_shr:2 row_mask:0xf bank_mask:0xf bound_ctrl:1
	v_fmac_f32_dpp v237, v79, v107 row_shr:2 row_mask:0xf bank_mask:0xf bound_ctrl:1
	v_fmac_f32_dpp v238, v80, v108 row_shr:2 row_mask:0xf bank_mask:0xf bound_ctrl:1
	v_fmac_f32_dpp v239, v81, v109 row_shr:2 row_mask:0xf bank_mask:0xf bound_ctrl:1
	v_fmac_f32_dpp v240, v74, v110 row_shr:2 row_mask:0xf bank_mask:0xf bound_ctrl:1
	v_fmac_f32_dpp v241, v75, v111 row_shr:2 row_mask:0xf bank_mask:0xf bound_ctrl:1
	v_fmac_f32_dpp v242, v76, v112 row_shr:2 row_mask:0xf bank_mask:0xf bound_ctrl:1
	v_fmac_f32_dpp v243, v77, v113 row_shr:2 row_mask:0xf bank_mask:0xf bound_ctrl:1
	v_fmac_f32_dpp v236, v94, v114 row_shl:15 row_mask:0xf bank_mask:0xf bound_ctrl:1
	v_fmac_f32_dpp v237, v95, v115 row_shl:15 row_mask:0xf bank_mask:0xf bound_ctrl:1
	v_fmac_f32_dpp v238, v96, v116 row_shl:15 row_mask:0xf bank_mask:0xf bound_ctrl:1
	v_fmac_f32_dpp v239, v97, v117 row_shl:15 row_mask:0xf bank_mask:0xf bound_ctrl:1
	v_fmac_f32_dpp v240, v90, v118 row_shl:15 row_mask:0xf bank_mask:0xf bound_ctrl:1
	v_fmac_f32_dpp v241, v91, v119 row_shl:15 row_mask:0xf bank_mask:0xf bound_ctrl:1
	v_fmac_f32_dpp v242, v92, v120 row_shl:15 row_mask:0xf bank_mask:0xf bound_ctrl:1
	v_fmac_f32_dpp v243, v93, v121 row_shl:15 row_mask:0xf bank_mask:0xf bound_ctrl:1
	v_fmac_f32_dpp v236, v94, v106 row_shl:14 row_mask:0xf bank_mask:0xf bound_ctrl:1
	v_fmac_f32_dpp v237, v95, v107 row_shl:14 row_mask:0xf bank_mask:0xf bound_ctrl:1
	v_fmac_f32_dpp v238, v96, v108 row_shl:14 row_mask:0xf bank_mask:0xf bound_ctrl:1
	v_fmac_f32_dpp v239, v97, v109 row_shl:14 row_mask:0xf bank_mask:0xf bound_ctrl:1
	v_fmac_f32_dpp v240, v90, v110 row_shl:14 row_mask:0xf bank_mask:0xf bound_ctrl:1
	v_fmac_f32_dpp v241, v91, v111 row_shl:14 row_mask:0xf bank_mask:0xf bound_ctrl:1
	v_fmac_f32_dpp v242, v92, v112 row_shl:14 row_mask:0xf bank_mask:0xf bound_ctrl:1
	v_fmac_f32_dpp v243, v93, v113 row_shl:14 row_mask:0xf bank_mask:0xf bound_ctrl:1
	v_pk_mul_f32 v[244:245], v[236:237], s[92:93] op_sel_hi:[1,0]
	v_pk_mul_f32 v[246:247], v[238:239], s[92:93] op_sel_hi:[1,0]
	v_pk_mul_f32 v[248:249], v[240:241], s[92:93] op_sel_hi:[1,0]
	v_pk_mul_f32 v[250:251], v[242:243], s[92:93] op_sel_hi:[1,0]
	v_exp_f32_e32 v244, v244
	v_exp_f32_e32 v245, v245
	v_exp_f32_e32 v246, v246
	v_exp_f32_e32 v247, v247
	v_exp_f32_e32 v248, v248
	v_exp_f32_e32 v249, v249
	v_exp_f32_e32 v250, v250
	v_exp_f32_e32 v251, v251
	v_pk_mul_f32 v[236:237], v[236:237], v[70:71]
	v_pk_mul_f32 v[238:239], v[238:239], v[72:73]
	v_pk_mul_f32 v[240:241], v[240:241], v[66:67]
	v_pk_mul_f32 v[242:243], v[242:243], v[68:69]
	v_pk_add_f32 v[244:245], v[244:245], 1.0 op_sel_hi:[1,0]
	v_pk_add_f32 v[246:247], v[246:247], 1.0 op_sel_hi:[1,0]
	v_pk_add_f32 v[248:249], v[248:249], 1.0 op_sel_hi:[1,0]
	v_pk_add_f32 v[250:251], v[250:251], 1.0 op_sel_hi:[1,0]
	v_rcp_f32_e32 v244, v244
	v_rcp_f32_e32 v245, v245
	v_rcp_f32_e32 v246, v246
	v_rcp_f32_e32 v247, v247
	v_rcp_f32_e32 v248, v248
	v_rcp_f32_e32 v249, v249
	v_rcp_f32_e32 v250, v250
	v_rcp_f32_e32 v251, v251
	s_nop 0
	v_pk_mul_f32 v[236:237], v[236:237], v[244:245]
	v_pk_mul_f32 v[238:239], v[238:239], v[246:247]
	v_pk_mul_f32 v[240:241], v[240:241], v[248:249]
	v_pk_mul_f32 v[242:243], v[242:243], v[250:251]
	v_cvt_pk_bf16_f32 v216, v236, v237
	v_cvt_pk_bf16_f32 v217, v238, v239
;     __device__ __forceinline__ void operator()(const f32x4 (&acc)[2][2][4][2], const Unit& u, int wr, int wc, int fr, int fq) const {
;     ...
;             for (int m = 0; m < 4; ++m) {
;                 const int row = row0 + ai * HALF + m * 16; const float rs = rsv[m];
;                 const f32x4 ca = acc[ai][0][m][0] * rs, cb_ = acc[ai][0][m][1] * rs;
;                 f32x4 aa = w2a * ca + ba, ab = w2b * cb_ + bb;
; #pragma unroll
;                 for (int c = 0; c < 4; ++c) { aa[c] = __builtin_fmaf(w1a[c], dpp_shr1(ca[c]), aa[c]); ab[c] = __builtin_fmaf(w1b[c], dpp_shr1(cb_[c]), ab[c]);
;                     aa[c] = __builtin_fmaf(w0a[c], dpp_shr2(ca[c]), aa[c]); ab[c] = __builtin_fmaf(w0b[c], dpp_shr2(cb_[c]), ab[c]); }
;                 if (m == 0) {
;                     if (ai == 1 || wr == 1) { const int sw = ((ai == 1 && wr == 0) ? 4 : 0) + wc, sai = (ai == 1 && wr == 1) ? 1 : 0;
;                         const PG8_LAS f32x4* xp = (const PG8_LAS f32x4*)(X + ((sw * 2 + sai) * 2) * 32 + fq * 8); const f32x4 h0a = xp[0], h0b = xp[1], h1a = xp[8], h1b = xp[9];
;                         aa += w1a * (h1a * m0) + w0a * (h0a * m0 + h1a * m1); ab += w1b * (h1b * m0) + w0b * (h0b * m0 + h1b * m1); }
;                 } else {
; #pragma unroll
;                     for (int c = 0; c < 4; ++c) { aa[c] = __builtin_fmaf(w1a[c], dpp_shl15(pa[c]), aa[c]); ab[c] = __builtin_fmaf(w1b[c], dpp_shl15(pb[c]), ab[c]);
;                         aa[c] = __builtin_fmaf(w0a[c], dpp_shl14(pa[c]), aa[c]); ab[c] = __builtin_fmaf(w0b[c], dpp_shl14(pb[c]), ab[c]); }
;                 }
;                 const f32x4 ga = acc[ai][1][m][0] * rs, gb = acc[ai][1][m][1] * rs;
;                 f32x4 ea = aa * -1.4426950408889634f, eb = ab * -1.4426950408889634f;
; #pragma unroll
;                 for (int c = 0; c < 4; ++c) { ea[c] = __builtin_amdgcn_exp2f(ea[c]); eb[c] = __builtin_amdgcn_exp2f(eb[c]); }
;                 ea = ea + 1.0f; eb = eb + 1.0f;
; #pragma unroll
;                 for (int c = 0; c < 4; ++c) { ea[c] = __builtin_amdgcn_rcpf(ea[c]); eb[c] = __builtin_amdgcn_rcpf(eb[c]); }
;                 const f32x4 oa = (aa * ga) * ea, ob = (ab * gb) * eb;
;                 u32x4 w; w.x = cvt_pk_bf16(oa[0], oa[1]); w.y = cvt_pk_bf16(oa[2], oa[3]); w.z = cvt_pk_bf16(ob[0], ob[1]); w.w = cvt_pk_bf16(ob[2], ob[3]);
;                 *(u32x4*)(act + (size_t)row * FF + col) = w;
	v_cvt_pk_bf16_f32 v218, v240, v241
	v_cvt_pk_bf16_f32 v219, v242, v243
	global_store_dwordx4 v[220:221], v[216:219], off
	v_lshl_add_u64 v[220:221], v[220:221], 0, s[98:99]
	v_pk_mul_f32 v[62:63], v[62:63], v[170:171] op_sel_hi:[1,0]
	v_pk_mul_f32 v[64:65], v[64:65], v[170:171] op_sel_hi:[1,0]
	v_pk_mul_f32 v[58:59], v[58:59], v[170:171] op_sel_hi:[1,0]
	v_pk_mul_f32 v[60:61], v[60:61], v[170:171] op_sel_hi:[1,0]
	v_lshl_add_u32 v167, v163, 2, s64
	ds_read_b128 v[192:195], v167
	ds_read_b128 v[196:199], v167 offset:16
	ds_read_b128 v[200:203], v167 offset:128
	ds_read_b128 v[204:207], v167 offset:144
	v_pk_fma_f32 v[236:237], v[122:123], v[62:63], v[130:131]
	v_pk_fma_f32 v[238:239], v[124:125], v[64:65], v[132:133]
	v_pk_fma_f32 v[240:241], v[126:127], v[58:59], v[134:135]
	v_pk_fma_f32 v[242:243], v[128:129], v[60:61], v[136:137]
	v_pk_mul_f32 v[54:55], v[54:55], v[170:171] op_sel_hi:[1,0]
	v_pk_mul_f32 v[56:57], v[56:57], v[170:171] op_sel_hi:[1,0]
	v_pk_mul_f32 v[50:51], v[50:51], v[170:171] op_sel_hi:[1,0]
	v_pk_mul_f32 v[52:53], v[52:53], v[170:171] op_sel_hi:[1,0]
	v_fmac_f32_dpp v236, v62, v114 row_shr:1 row_mask:0xf bank_mask:0xf bound_ctrl:1
	v_fmac_f32_dpp v237, v63, v115 row_shr:1 row_mask:0xf bank_mask:0xf bound_ctrl:1
	v_fmac_f32_dpp v238, v64, v116 row_shr:1 row_mask:0xf bank_mask:0xf bound_ctrl:1
	v_fmac_f32_dpp v239, v65, v117 row_shr:1 row_mask:0xf bank_mask:0xf bound_ctrl:1
	v_fmac_f32_dpp v240, v58, v118 row_shr:1 row_mask:0xf bank_mask:0xf bound_ctrl:1
	v_fmac_f32_dpp v241, v59, v119 row_shr:1 row_mask:0xf bank_mask:0xf bound_ctrl:1
	v_fmac_f32_dpp v242, v60, v120 row_shr:1 row_mask:0xf bank_mask:0xf bound_ctrl:1
	v_fmac_f32_dpp v243, v61, v121 row_shr:1 row_mask:0xf bank_mask:0xf bound_ctrl:1
	v_fmac_f32_dpp v236, v62, v106 row_shr:2 row_mask:0xf bank_mask:0xf bound_ctrl:1
	v_fmac_f32_dpp v237, v63, v107 row_shr:2 row_mask:0xf bank_mask:0xf bound_ctrl:1
	v_fmac_f32_dpp v238, v64, v108 row_shr:2 row_mask:0xf bank_mask:0xf bound_ctrl:1
	v_fmac_f32_dpp v239, v65, v109 row_shr:2 row_mask:0xf bank_mask:0xf bound_ctrl:1
	v_fmac_f32_dpp v240, v58, v110 row_shr:2 row_mask:0xf bank_mask:0xf bound_ctrl:1
	v_fmac_f32_dpp v241, v59, v111 row_shr:2 row_mask:0xf bank_mask:0xf bound_ctrl:1
	v_fmac_f32_dpp v242, v60, v112 row_shr:2 row_mask:0xf bank_mask:0xf bound_ctrl:1
	v_fmac_f32_dpp v243, v61, v113 row_shr:2 row_mask:0xf bank_mask:0xf bound_ctrl:1
	v_cmp_eq_u32_e64 s[44:45], 0, v1
	v_cmp_eq_u32_e64 s[46:47], 1, v1
	s_waitcnt lgkmcnt(0)
	s_mov_b64 exec, s[44:45]
	v_pk_fma_f32 v[236:237], v[114:115], v[200:201], v[236:237]
	v_pk_fma_f32 v[238:239], v[116:117], v[202:203], v[238:239]
	v_pk_fma_f32 v[240:241], v[118:119], v[204:205], v[240:241]
	v_pk_fma_f32 v[242:243], v[120:121], v[206:207], v[242:243]
	v_pk_fma_f32 v[236:237], v[106:107], v[192:193], v[236:237]
	v_pk_fma_f32 v[238:239], v[108:109], v[194:195], v[238:239]
	v_pk_fma_f32 v[240:241], v[110:111], v[196:197], v[240:241]
	v_pk_fma_f32 v[242:243], v[112:113], v[198:199], v[242:243]
	s_mov_b64 exec, s[46:47]
	v_pk_fma_f32 v[236:237], v[106:107], v[200:201], v[236:237]
	v_pk_fma_f32 v[238:239], v[108:109], v[202:203], v[238:239]
	v_pk_fma_f32 v[240:241], v[110:111], v[204:205], v[240:241]
	v_pk_fma_f32 v[242:243], v[112:113], v[206:207], v[242:243]
	s_mov_b64 exec, -1
	v_pk_mul_f32 v[244:245], v[236:237], s[92:93] op_sel_hi:[1,0]
	v_pk_mul_f32 v[246:247], v[238:239], s[92:93] op_sel_hi:[1,0]
	v_pk_mul_f32 v[248:249], v[240:241], s[92:93] op_sel_hi:[1,0]
	v_pk_mul_f32 v[250:251], v[242:243], s[92:93] op_sel_hi:[1,0]
	v_exp_f32_e32 v244, v244
	v_exp_f32_e32 v245, v245
	v_exp_f32_e32 v246, v246
	v_exp_f32_e32 v247, v247
	v_exp_f32_e32 v248, v248
	v_exp_f32_e32 v249, v249
	v_exp_f32_e32 v250, v250
	v_exp_f32_e32 v251, v251
	v_pk_mul_f32 v[236:237], v[236:237], v[54:55]
	v_pk_mul_f32 v[238:239], v[238:239], v[56:57]
	v_pk_mul_f32 v[240:241], v[240:241], v[50:51]
	v_pk_mul_f32 v[242:243], v[242:243], v[52:53]
	v_pk_add_f32 v[244:245], v[244:245], 1.0 op_sel_hi:[1,0]
	v_pk_add_f32 v[246:247], v[246:247], 1.0 op_sel_hi:[1,0]
	v_pk_add_f32 v[248:249], v[248:249], 1.0 op_sel_hi:[1,0]
	v_pk_add_f32 v[250:251], v[250:251], 1.0 op_sel_hi:[1,0]
	v_rcp_f32_e32 v244, v244
	v_rcp_f32_e32 v245, v245
	v_rcp_f32_e32 v246, v246
	v_rcp_f32_e32 v247, v247
	v_rcp_f32_e32 v248, v248
	v_rcp_f32_e32 v249, v249
	v_rcp_f32_e32 v250, v250
	v_rcp_f32_e32 v251, v251
	s_nop 0
	v_pk_mul_f32 v[236:237], v[236:237], v[244:245]
	v_pk_mul_f32 v[238:239], v[238:239], v[246:247]
	v_pk_mul_f32 v[240:241], v[240:241], v[248:249]
	v_pk_mul_f32 v[242:243], v[242:243], v[250:251]
	v_cvt_pk_bf16_f32 v216, v236, v237
	v_cvt_pk_bf16_f32 v217, v238, v239
	v_cvt_pk_bf16_f32 v218, v240, v241
	v_cvt_pk_bf16_f32 v219, v242, v243
	global_store_dwordx4 v[220:221], v[216:219], off
	v_lshl_add_u64 v[220:221], v[220:221], 0, s[100:101]
	v_pk_mul_f32 v[46:47], v[46:47], v[172:173] op_sel_hi:[1,0]
	v_pk_mul_f32 v[48:49], v[48:49], v[172:173] op_sel_hi:[1,0]
	v_pk_mul_f32 v[42:43], v[42:43], v[172:173] op_sel_hi:[1,0]
	v_pk_mul_f32 v[44:45], v[44:45], v[172:173] op_sel_hi:[1,0]
	v_pk_fma_f32 v[236:237], v[122:123], v[46:47], v[130:131]
	v_pk_fma_f32 v[238:239], v[124:125], v[48:49], v[132:133]
	v_pk_fma_f32 v[240:241], v[126:127], v[42:43], v[134:135]
	v_pk_fma_f32 v[242:243], v[128:129], v[44:45], v[136:137]
	v_pk_mul_f32 v[38:39], v[38:39], v[172:173] op_sel_hi:[1,0]
	v_pk_mul_f32 v[40:41], v[40:41], v[172:173] op_sel_hi:[1,0]
	v_pk_mul_f32 v[34:35], v[34:35], v[172:173] op_sel_hi:[1,0]
	v_pk_mul_f32 v[36:37], v[36:37], v[172:173] op_sel_hi:[1,0]
	v_fmac_f32_dpp v236, v46, v114 row_shr:1 row_mask:0xf bank_mask:0xf bound_ctrl:1
;     __device__ __forceinline__ void operator()(const f32x4 (&acc)[2][2][4][2], const Unit& u, int wr, int wc, int fr, int fq) const {
;     ...
;             for (int m = 0; m < 4; ++m) {
;                 const int row = row0 + ai * HALF + m * 16; const float rs = rsv[m];
;                 const f32x4 ca = acc[ai][0][m][0] * rs, cb_ = acc[ai][0][m][1] * rs;
;                 f32x4 aa = w2a * ca + ba, ab = w2b * cb_ + bb;
; #pragma unroll
;                 for (int c = 0; c < 4; ++c) { aa[c] = __builtin_fmaf(w1a[c], dpp_shr1(ca[c]), aa[c]); ab[c] = __builtin_fmaf(w1b[c], dpp_shr1(cb_[c]), ab[c]);
;                     aa[c] = __builtin_fmaf(w0a[c], dpp_shr2(ca[c]), aa[c]); ab[c] = __builtin_fmaf(w0b[c], dpp_shr2(cb_[c]), ab[c]); }
;                 if (m == 0) {
;                     if (ai == 1 || wr == 1) { const int sw = ((ai == 1 && wr == 0) ? 4 : 0) + wc, sai = (ai == 1 && wr == 1) ? 1 : 0;
;                         const PG8_LAS f32x4* xp = (const PG8_LAS f32x4*)(X + ((sw * 2 + sai) * 2) * 32 + fq * 8); const f32x4 h0a = xp[0], h0b = xp[1], h1a = xp[8], h1b = xp[9];
;                         aa += w1a * (h1a * m0) + w0a * (h0a * m0 + h1a * m1); ab += w1b * (h1b * m0) + w0b * (h0b * m0 + h1b * m1); }
;                 } else {
; #pragma unroll
;                     for (int c = 0; c < 4; ++c) { aa[c] = __builtin_fmaf(w1a[c], dpp_shl15(pa[c]), aa[c]); ab[c] = __builtin_fmaf(w1b[c], dpp_shl15(pb[c]), ab[c]);
;                         aa[c] = __builtin_fmaf(w0a[c], dpp_shl14(pa[c]), aa[c]); ab[c] = __builtin_fmaf(w0b[c], dpp_shl14(pb[c]), ab[c]); }
;                 }
;                 const f32x4 ga = acc[ai][1][m][0] * rs, gb = acc[ai][1][m][1] * rs;
;                 f32x4 ea = aa * -1.4426950408889634f, eb = ab * -1.4426950408889634f;
; #pragma unroll
;                 for (int c = 0; c < 4; ++c) { ea[c] = __builtin_amdgcn_exp2f(ea[c]); eb[c] = __builtin_amdgcn_exp2f(eb[c]); }
;                 ea = ea + 1.0f; eb = eb + 1.0f;
; #pragma unroll
;                 for (int c = 0; c < 4; ++c) { ea[c] = __builtin_amdgcn_rcpf(ea[c]); eb[c] = __builtin_amdgcn_rcpf(eb[c]); }
;                 const f32x4 oa = (aa * ga) * ea, ob = (ab * gb) * eb;
;                 u32x4 w; w.x = cvt_pk_bf16(oa[0], oa[1]); w.y = cvt_pk_bf16(oa[2], oa[3]); w.z = cvt_pk_bf16(ob[0], ob[1]); w.w = cvt_pk_bf16(ob[2], ob[3]);
;                 *(u32x4*)(act + (size_t)row * FF + col) = w;
	v_fmac_f32_dpp v237, v47, v115 row_shr:1 row_mask:0xf bank_mask:0xf bound_ctrl:1
	v_fmac_f32_dpp v238, v48, v116 row_shr:1 row_mask:0xf bank_mask:0xf bound_ctrl:1
	v_fmac_f32_dpp v239, v49, v117 row_shr:1 row_mask:0xf bank_mask:0xf bound_ctrl:1
	v_fmac_f32_dpp v240, v42, v118 row_shr:1 row_mask:0xf bank_mask:0xf bound_ctrl:1
	v_fmac_f32_dpp v241, v43, v119 row_shr:1 row_mask:0xf bank_mask:0xf bound_ctrl:1
	v_fmac_f32_dpp v242, v44, v120 row_shr:1 row_mask:0xf bank_mask:0xf bound_ctrl:1
	v_fmac_f32_dpp v243, v45, v121 row_shr:1 row_mask:0xf bank_mask:0xf bound_ctrl:1
	v_fmac_f32_dpp v236, v46, v106 row_shr:2 row_mask:0xf bank_mask:0xf bound_ctrl:1
	v_fmac_f32_dpp v237, v47, v107 row_shr:2 row_mask:0xf bank_mask:0xf bound_ctrl:1
	v_fmac_f32_dpp v238, v48, v108 row_shr:2 row_mask:0xf bank_mask:0xf bound_ctrl:1
	v_fmac_f32_dpp v239, v49, v109 row_shr:2 row_mask:0xf bank_mask:0xf bound_ctrl:1
	v_fmac_f32_dpp v240, v42, v110 row_shr:2 row_mask:0xf bank_mask:0xf bound_ctrl:1
	v_fmac_f32_dpp v241, v43, v111 row_shr:2 row_mask:0xf bank_mask:0xf bound_ctrl:1
	v_fmac_f32_dpp v242, v44, v112 row_shr:2 row_mask:0xf bank_mask:0xf bound_ctrl:1
	v_fmac_f32_dpp v243, v45, v113 row_shr:2 row_mask:0xf bank_mask:0xf bound_ctrl:1
	v_fmac_f32_dpp v236, v62, v114 row_shl:15 row_mask:0xf bank_mask:0xf bound_ctrl:1
	v_fmac_f32_dpp v237, v63, v115 row_shl:15 row_mask:0xf bank_mask:0xf bound_ctrl:1
	v_fmac_f32_dpp v238, v64, v116 row_shl:15 row_mask:0xf bank_mask:0xf bound_ctrl:1
	v_fmac_f32_dpp v239, v65, v117 row_shl:15 row_mask:0xf bank_mask:0xf bound_ctrl:1
	v_fmac_f32_dpp v240, v58, v118 row_shl:15 row_mask:0xf bank_mask:0xf bound_ctrl:1
	v_fmac_f32_dpp v241, v59, v119 row_shl:15 row_mask:0xf bank_mask:0xf bound_ctrl:1
	v_fmac_f32_dpp v242, v60, v120 row_shl:15 row_mask:0xf bank_mask:0xf bound_ctrl:1
	v_fmac_f32_dpp v243, v61, v121 row_shl:15 row_mask:0xf bank_mask:0xf bound_ctrl:1
	v_fmac_f32_dpp v236, v62, v106 row_shl:14 row_mask:0xf bank_mask:0xf bound_ctrl:1
	v_fmac_f32_dpp v237, v63, v107 row_shl:14 row_mask:0xf bank_mask:0xf bound_ctrl:1
	v_fmac_f32_dpp v238, v64, v108 row_shl:14 row_mask:0xf bank_mask:0xf bound_ctrl:1
	v_fmac_f32_dpp v239, v65, v109 row_shl:14 row_mask:0xf bank_mask:0xf bound_ctrl:1
	v_fmac_f32_dpp v240, v58, v110 row_shl:14 row_mask:0xf bank_mask:0xf bound_ctrl:1
	v_fmac_f32_dpp v241, v59, v111 row_shl:14 row_mask:0xf bank_mask:0xf bound_ctrl:1
	v_fmac_f32_dpp v242, v60, v112 row_shl:14 row_mask:0xf bank_mask:0xf bound_ctrl:1
	v_fmac_f32_dpp v243, v61, v113 row_shl:14 row_mask:0xf bank_mask:0xf bound_ctrl:1
	v_pk_mul_f32 v[244:245], v[236:237], s[92:93] op_sel_hi:[1,0]
	v_pk_mul_f32 v[246:247], v[238:239], s[92:93] op_sel_hi:[1,0]
	v_pk_mul_f32 v[248:249], v[240:241], s[92:93] op_sel_hi:[1,0]
	v_pk_mul_f32 v[250:251], v[242:243], s[92:93] op_sel_hi:[1,0]
	v_exp_f32_e32 v244, v244
	v_exp_f32_e32 v245, v245
	v_exp_f32_e32 v246, v246
	v_exp_f32_e32 v247, v247
	v_exp_f32_e32 v248, v248
	v_exp_f32_e32 v249, v249
	v_exp_f32_e32 v250, v250
	v_exp_f32_e32 v251, v251
	v_pk_mul_f32 v[236:237], v[236:237], v[38:39]
	v_pk_mul_f32 v[238:239], v[238:239], v[40:41]
	v_pk_mul_f32 v[240:241], v[240:241], v[34:35]
	v_pk_mul_f32 v[242:243], v[242:243], v[36:37]
	v_pk_add_f32 v[244:245], v[244:245], 1.0 op_sel_hi:[1,0]
	v_pk_add_f32 v[246:247], v[246:247], 1.0 op_sel_hi:[1,0]
	v_pk_add_f32 v[248:249], v[248:249], 1.0 op_sel_hi:[1,0]
	v_pk_add_f32 v[250:251], v[250:251], 1.0 op_sel_hi:[1,0]
	v_rcp_f32_e32 v244, v244
	v_rcp_f32_e32 v245, v245
	v_rcp_f32_e32 v246, v246
	v_rcp_f32_e32 v247, v247
	v_rcp_f32_e32 v248, v248
	v_rcp_f32_e32 v249, v249
	v_rcp_f32_e32 v250, v250
	v_rcp_f32_e32 v251, v251
	s_nop 0
	v_pk_mul_f32 v[236:237], v[236:237], v[244:245]
	v_pk_mul_f32 v[238:239], v[238:239], v[246:247]
	v_pk_mul_f32 v[240:241], v[240:241], v[248:249]
	v_pk_mul_f32 v[242:243], v[242:243], v[250:251]
	v_cvt_pk_bf16_f32 v216, v236, v237
	v_cvt_pk_bf16_f32 v217, v238, v239
	v_cvt_pk_bf16_f32 v218, v240, v241
	v_cvt_pk_bf16_f32 v219, v242, v243
	global_store_dwordx4 v[220:221], v[216:219], off
	v_lshl_add_u64 v[220:221], v[220:221], 0, s[100:101]
	v_pk_mul_f32 v[30:31], v[30:31], v[232:233] op_sel_hi:[1,0]
	v_pk_mul_f32 v[32:33], v[32:33], v[232:233] op_sel_hi:[1,0]
	v_pk_mul_f32 v[26:27], v[26:27], v[232:233] op_sel_hi:[1,0]
	v_pk_mul_f32 v[28:29], v[28:29], v[232:233] op_sel_hi:[1,0]
	v_pk_fma_f32 v[236:237], v[122:123], v[30:31], v[130:131]
	v_pk_fma_f32 v[238:239], v[124:125], v[32:33], v[132:133]
	v_pk_fma_f32 v[240:241], v[126:127], v[26:27], v[134:135]
	v_pk_fma_f32 v[242:243], v[128:129], v[28:29], v[136:137]
	v_pk_mul_f32 v[22:23], v[22:23], v[232:233] op_sel_hi:[1,0]
	v_pk_mul_f32 v[24:25], v[24:25], v[232:233] op_sel_hi:[1,0]
	v_pk_mul_f32 v[18:19], v[18:19], v[232:233] op_sel_hi:[1,0]
	v_pk_mul_f32 v[20:21], v[20:21], v[232:233] op_sel_hi:[1,0]
	v_fmac_f32_dpp v236, v30, v114 row_shr:1 row_mask:0xf bank_mask:0xf bound_ctrl:1
	v_fmac_f32_dpp v237, v31, v115 row_shr:1 row_mask:0xf bank_mask:0xf bound_ctrl:1
	v_fmac_f32_dpp v238, v32, v116 row_shr:1 row_mask:0xf bank_mask:0xf bound_ctrl:1
	v_fmac_f32_dpp v239, v33, v117 row_shr:1 row_mask:0xf bank_mask:0xf bound_ctrl:1
	v_fmac_f32_dpp v240, v26, v118 row_shr:1 row_mask:0xf bank_mask:0xf bound_ctrl:1
	v_fmac_f32_dpp v241, v27, v119 row_shr:1 row_mask:0xf bank_mask:0xf bound_ctrl:1
	v_fmac_f32_dpp v242, v28, v120 row_shr:1 row_mask:0xf bank_mask:0xf bound_ctrl:1
	v_fmac_f32_dpp v243, v29, v121 row_shr:1 row_mask:0xf bank_mask:0xf bound_ctrl:1
	v_fmac_f32_dpp v236, v30, v106 row_shr:2 row_mask:0xf bank_mask:0xf bound_ctrl:1
	v_fmac_f32_dpp v237, v31, v107 row_shr:2 row_mask:0xf bank_mask:0xf bound_ctrl:1
;     __device__ __forceinline__ void operator()(const f32x4 (&acc)[2][2][4][2], const Unit& u, int wr, int wc, int fr, int fq) const {
;     ...
;             for (int m = 0; m < 4; ++m) {
;                 const int row = row0 + ai * HALF + m * 16; const float rs = rsv[m];
;                 const f32x4 ca = acc[ai][0][m][0] * rs, cb_ = acc[ai][0][m][1] * rs;
;                 f32x4 aa = w2a * ca + ba, ab = w2b * cb_ + bb;
; #pragma unroll
;                 for (int c = 0; c < 4; ++c) { aa[c] = __builtin_fmaf(w1a[c], dpp_shr1(ca[c]), aa[c]); ab[c] = __builtin_fmaf(w1b[c], dpp_shr1(cb_[c]), ab[c]);
;                     aa[c] = __builtin_fmaf(w0a[c], dpp_shr2(ca[c]), aa[c]); ab[c] = __builtin_fmaf(w0b[c], dpp_shr2(cb_[c]), ab[c]); }
;                 if (m == 0) {
;                     if (ai == 1 || wr == 1) { const int sw = ((ai == 1 && wr == 0) ? 4 : 0) + wc, sai = (ai == 1 && wr == 1) ? 1 : 0;
;                         const PG8_LAS f32x4* xp = (const PG8_LAS f32x4*)(X + ((sw * 2 + sai) * 2) * 32 + fq * 8); const f32x4 h0a = xp[0], h0b = xp[1], h1a = xp[8], h1b = xp[9];
;                         aa += w1a * (h1a * m0) + w0a * (h0a * m0 + h1a * m1); ab += w1b * (h1b * m0) + w0b * (h0b * m0 + h1b * m1); }
;                 } else {
; #pragma unroll
;                     for (int c = 0; c < 4; ++c) { aa[c] = __builtin_fmaf(w1a[c], dpp_shl15(pa[c]), aa[c]); ab[c] = __builtin_fmaf(w1b[c], dpp_shl15(pb[c]), ab[c]);
;                         aa[c] = __builtin_fmaf(w0a[c], dpp_shl14(pa[c]), aa[c]); ab[c] = __builtin_fmaf(w0b[c], dpp_shl14(pb[c]), ab[c]); }
;                 }
;                 const f32x4 ga = acc[ai][1][m][0] * rs, gb = acc[ai][1][m][1] * rs;
;                 f32x4 ea = aa * -1.4426950408889634f, eb = ab * -1.4426950408889634f;
; #pragma unroll
;                 for (int c = 0; c < 4; ++c) { ea[c] = __builtin_amdgcn_exp2f(ea[c]); eb[c] = __builtin_amdgcn_exp2f(eb[c]); }
;                 ea = ea + 1.0f; eb = eb + 1.0f;
; #pragma unroll
;                 for (int c = 0; c < 4; ++c) { ea[c] = __builtin_amdgcn_rcpf(ea[c]); eb[c] = __builtin_amdgcn_rcpf(eb[c]); }
;                 const f32x4 oa = (aa * ga) * ea, ob = (ab * gb) * eb;
;                 u32x4 w; w.x = cvt_pk_bf16(oa[0], oa[1]); w.y = cvt_pk_bf16(oa[2], oa[3]); w.z = cvt_pk_bf16(ob[0], ob[1]); w.w = cvt_pk_bf16(ob[2], ob[3]);
;                 *(u32x4*)(act + (size_t)row * FF + col) = w;
	v_fmac_f32_dpp v238, v32, v108 row_shr:2 row_mask:0xf bank_mask:0xf bound_ctrl:1
	v_fmac_f32_dpp v239, v33, v109 row_shr:2 row_mask:0xf bank_mask:0xf bound_ctrl:1
	v_fmac_f32_dpp v240, v26, v110 row_shr:2 row_mask:0xf bank_mask:0xf bound_ctrl:1
	v_fmac_f32_dpp v241, v27, v111 row_shr:2 row_mask:0xf bank_mask:0xf bound_ctrl:1
	v_fmac_f32_dpp v242, v28, v112 row_shr:2 row_mask:0xf bank_mask:0xf bound_ctrl:1
	v_fmac_f32_dpp v243, v29, v113 row_shr:2 row_mask:0xf bank_mask:0xf bound_ctrl:1
	v_fmac_f32_dpp v236, v46, v114 row_shl:15 row_mask:0xf bank_mask:0xf bound_ctrl:1
	v_fmac_f32_dpp v237, v47, v115 row_shl:15 row_mask:0xf bank_mask:0xf bound_ctrl:1
	v_fmac_f32_dpp v238, v48, v116 row_shl:15 row_mask:0xf bank_mask:0xf bound_ctrl:1
	v_fmac_f32_dpp v239, v49, v117 row_shl:15 row_mask:0xf bank_mask:0xf bound_ctrl:1
	v_fmac_f32_dpp v240, v42, v118 row_shl:15 row_mask:0xf bank_mask:0xf bound_ctrl:1
	v_fmac_f32_dpp v241, v43, v119 row_shl:15 row_mask:0xf bank_mask:0xf bound_ctrl:1
	v_fmac_f32_dpp v242, v44, v120 row_shl:15 row_mask:0xf bank_mask:0xf bound_ctrl:1
	v_fmac_f32_dpp v243, v45, v121 row_shl:15 row_mask:0xf bank_mask:0xf bound_ctrl:1
	v_fmac_f32_dpp v236, v46, v106 row_shl:14 row_mask:0xf bank_mask:0xf bound_ctrl:1
	v_fmac_f32_dpp v237, v47, v107 row_shl:14 row_mask:0xf bank_mask:0xf bound_ctrl:1
	v_fmac_f32_dpp v238, v48, v108 row_shl:14 row_mask:0xf bank_mask:0xf bound_ctrl:1
	v_fmac_f32_dpp v239, v49, v109 row_shl:14 row_mask:0xf bank_mask:0xf bound_ctrl:1
	v_fmac_f32_dpp v240, v42, v110 row_shl:14 row_mask:0xf bank_mask:0xf bound_ctrl:1
	v_fmac_f32_dpp v241, v43, v111 row_shl:14 row_mask:0xf bank_mask:0xf bound_ctrl:1
	v_fmac_f32_dpp v242, v44, v112 row_shl:14 row_mask:0xf bank_mask:0xf bound_ctrl:1
	v_fmac_f32_dpp v243, v45, v113 row_shl:14 row_mask:0xf bank_mask:0xf bound_ctrl:1
	v_pk_mul_f32 v[244:245], v[236:237], s[92:93] op_sel_hi:[1,0]
	v_pk_mul_f32 v[246:247], v[238:239], s[92:93] op_sel_hi:[1,0]
	v_pk_mul_f32 v[248:249], v[240:241], s[92:93] op_sel_hi:[1,0]
	v_pk_mul_f32 v[250:251], v[242:243], s[92:93] op_sel_hi:[1,0]
	v_exp_f32_e32 v244, v244
	v_exp_f32_e32 v245, v245
	v_exp_f32_e32 v246, v246
	v_exp_f32_e32 v247, v247
	v_exp_f32_e32 v248, v248
	v_exp_f32_e32 v249, v249
	v_exp_f32_e32 v250, v250
	v_exp_f32_e32 v251, v251
	v_pk_mul_f32 v[236:237], v[236:237], v[22:23]
	v_pk_mul_f32 v[238:239], v[238:239], v[24:25]
	v_pk_mul_f32 v[240:241], v[240:241], v[18:19]
	v_pk_mul_f32 v[242:243], v[242:243], v[20:21]
	v_pk_add_f32 v[244:245], v[244:245], 1.0 op_sel_hi:[1,0]
	v_pk_add_f32 v[246:247], v[246:247], 1.0 op_sel_hi:[1,0]
	v_pk_add_f32 v[248:249], v[248:249], 1.0 op_sel_hi:[1,0]
	v_pk_add_f32 v[250:251], v[250:251], 1.0 op_sel_hi:[1,0]
	v_rcp_f32_e32 v244, v244
	v_rcp_f32_e32 v245, v245
	v_rcp_f32_e32 v246, v246
	v_rcp_f32_e32 v247, v247
	v_rcp_f32_e32 v248, v248
	v_rcp_f32_e32 v249, v249
	v_rcp_f32_e32 v250, v250
	v_rcp_f32_e32 v251, v251
	s_nop 0
	v_pk_mul_f32 v[236:237], v[236:237], v[244:245]
	v_pk_mul_f32 v[238:239], v[238:239], v[246:247]
	v_pk_mul_f32 v[240:241], v[240:241], v[248:249]
	v_pk_mul_f32 v[242:243], v[242:243], v[250:251]
	v_cvt_pk_bf16_f32 v216, v236, v237
	v_cvt_pk_bf16_f32 v217, v238, v239
	v_cvt_pk_bf16_f32 v218, v240, v241
	v_cvt_pk_bf16_f32 v219, v242, v243
	global_store_dwordx4 v[220:221], v[216:219], off
	v_lshl_add_u64 v[220:221], v[220:221], 0, s[100:101]
	v_pk_fma_f32 v[236:237], v[122:123], v[14:15], v[130:131]
	v_pk_fma_f32 v[238:239], v[124:125], v[16:17], v[132:133]
	v_pk_fma_f32 v[240:241], v[126:127], v[10:11], v[134:135]
	v_pk_fma_f32 v[242:243], v[128:129], v[12:13], v[136:137]
	v_pk_mul_f32 v[6:7], v[6:7], v[234:235] op_sel_hi:[1,0]
	v_pk_mul_f32 v[8:9], v[8:9], v[234:235] op_sel_hi:[1,0]
	v_pk_mul_f32 v[2:3], v[2:3], v[234:235] op_sel_hi:[1,0]
	v_pk_mul_f32 v[4:5], v[4:5], v[234:235] op_sel_hi:[1,0]
	v_fmac_f32_dpp v236, v14, v114 row_shr:1 row_mask:0xf bank_mask:0xf bound_ctrl:1
	v_fmac_f32_dpp v237, v15, v115 row_shr:1 row_mask:0xf bank_mask:0xf bound_ctrl:1
	v_fmac_f32_dpp v238, v16, v116 row_shr:1 row_mask:0xf bank_mask:0xf bound_ctrl:1
; __device__ __forceinline__ unsigned cvt_pk_bf16(float lo, float hi) { unsigned r; asm volatile("v_cvt_pk_bf16_f32 %0, %1, %2" : "=v"(r) : "v"(lo), "v"(hi)); return r; }
; #define PG8_BAR __builtin_amdgcn_s_barrier()
;     __device__ __forceinline__ void operator()(const f32x4 (&acc)[2][2][4][2], const Unit& u, int wr, int wc, int fr, int fq) const {
;     ...
;                 const f32x4 ga = acc[ai][1][m][0] * rs, gb = acc[ai][1][m][1] * rs;
;                 f32x4 ea = aa * -1.4426950408889634f, eb = ab * -1.4426950408889634f;
; #pragma unroll
;                 for (int c = 0; c < 4; ++c) { ea[c] = __builtin_amdgcn_exp2f(ea[c]); eb[c] = __builtin_amdgcn_exp2f(eb[c]); }
;                 ea = ea + 1.0f; eb = eb + 1.0f;
; #pragma unroll
;                 for (int c = 0; c < 4; ++c) { ea[c] = __builtin_amdgcn_rcpf(ea[c]); eb[c] = __builtin_amdgcn_rcpf(eb[c]); }
;                 const f32x4 oa = (aa * ga) * ea, ob = (ab * gb) * eb;
;                 u32x4 w; w.x = cvt_pk_bf16(oa[0], oa[1]); w.y = cvt_pk_bf16(oa[2], oa[3]); w.z = cvt_pk_bf16(ob[0], ob[1]); w.w = cvt_pk_bf16(ob[2], ob[3]);
;                 *(u32x4*)(act + (size_t)row * FF + col) = w;
; template <class Epi, class Sched, bool ALIGN_EPI = false, bool SP2 = false>
; __device__ __forceinline__ void gemm_phase(PG8_LAS unsigned char* lds, const Gemm g, const Sched& S, const Epi& E) {
;     ...
;         if (!has_next) break;
; #pragma unroll
;         for (int a = 0; a < 2; ++a)
; #pragma unroll
;             for (int b = 0; b < 2; ++b)
; #pragma unroll
;                 for (int m = 0; m < 4; ++m)
; #pragma unroll
;                     for (int n = 0; n < 2; ++n) acc[a][b][m][n] = (f32x4){0.f, 0.f, 0.f, 0.f};
;         cur = nxt; cA = nA; cB = nB; ++ui;
;         if constexpr (ALIGN_EPI) { if (wr == 1) PG8_BAR; }
	v_fmac_f32_dpp v239, v17, v117 row_shr:1 row_mask:0xf bank_mask:0xf bound_ctrl:1
	v_fmac_f32_dpp v240, v10, v118 row_shr:1 row_mask:0xf bank_mask:0xf bound_ctrl:1
	v_fmac_f32_dpp v241, v11, v119 row_shr:1 row_mask:0xf bank_mask:0xf bound_ctrl:1
	v_fmac_f32_dpp v242, v12, v120 row_shr:1 row_mask:0xf bank_mask:0xf bound_ctrl:1
	v_fmac_f32_dpp v243, v13, v121 row_shr:1 row_mask:0xf bank_mask:0xf bound_ctrl:1
	v_fmac_f32_dpp v236, v14, v106 row_shr:2 row_mask:0xf bank_mask:0xf bound_ctrl:1
	v_fmac_f32_dpp v237, v15, v107 row_shr:2 row_mask:0xf bank_mask:0xf bound_ctrl:1
	v_fmac_f32_dpp v238, v16, v108 row_shr:2 row_mask:0xf bank_mask:0xf bound_ctrl:1
	v_fmac_f32_dpp v239, v17, v109 row_shr:2 row_mask:0xf bank_mask:0xf bound_ctrl:1
	v_fmac_f32_dpp v240, v10, v110 row_shr:2 row_mask:0xf bank_mask:0xf bound_ctrl:1
	v_fmac_f32_dpp v241, v11, v111 row_shr:2 row_mask:0xf bank_mask:0xf bound_ctrl:1
	v_fmac_f32_dpp v242, v12, v112 row_shr:2 row_mask:0xf bank_mask:0xf bound_ctrl:1
	v_fmac_f32_dpp v243, v13, v113 row_shr:2 row_mask:0xf bank_mask:0xf bound_ctrl:1
	v_fmac_f32_dpp v236, v30, v114 row_shl:15 row_mask:0xf bank_mask:0xf bound_ctrl:1
	v_fmac_f32_dpp v237, v31, v115 row_shl:15 row_mask:0xf bank_mask:0xf bound_ctrl:1
	v_fmac_f32_dpp v238, v32, v116 row_shl:15 row_mask:0xf bank_mask:0xf bound_ctrl:1
	v_fmac_f32_dpp v239, v33, v117 row_shl:15 row_mask:0xf bank_mask:0xf bound_ctrl:1
	v_fmac_f32_dpp v240, v26, v118 row_shl:15 row_mask:0xf bank_mask:0xf bound_ctrl:1
	v_fmac_f32_dpp v241, v27, v119 row_shl:15 row_mask:0xf bank_mask:0xf bound_ctrl:1
	v_fmac_f32_dpp v242, v28, v120 row_shl:15 row_mask:0xf bank_mask:0xf bound_ctrl:1
	v_fmac_f32_dpp v243, v29, v121 row_shl:15 row_mask:0xf bank_mask:0xf bound_ctrl:1
	v_fmac_f32_dpp v236, v30, v106 row_shl:14 row_mask:0xf bank_mask:0xf bound_ctrl:1
	v_fmac_f32_dpp v237, v31, v107 row_shl:14 row_mask:0xf bank_mask:0xf bound_ctrl:1
	v_fmac_f32_dpp v238, v32, v108 row_shl:14 row_mask:0xf bank_mask:0xf bound_ctrl:1
	v_fmac_f32_dpp v239, v33, v109 row_shl:14 row_mask:0xf bank_mask:0xf bound_ctrl:1
	v_fmac_f32_dpp v240, v26, v110 row_shl:14 row_mask:0xf bank_mask:0xf bound_ctrl:1
	v_fmac_f32_dpp v241, v27, v111 row_shl:14 row_mask:0xf bank_mask:0xf bound_ctrl:1
	v_fmac_f32_dpp v242, v28, v112 row_shl:14 row_mask:0xf bank_mask:0xf bound_ctrl:1
	v_fmac_f32_dpp v243, v29, v113 row_shl:14 row_mask:0xf bank_mask:0xf bound_ctrl:1
	v_pk_mul_f32 v[244:245], v[236:237], s[92:93] op_sel_hi:[1,0]
	v_pk_mul_f32 v[246:247], v[238:239], s[92:93] op_sel_hi:[1,0]
	v_pk_mul_f32 v[248:249], v[240:241], s[92:93] op_sel_hi:[1,0]
	v_pk_mul_f32 v[250:251], v[242:243], s[92:93] op_sel_hi:[1,0]
	v_exp_f32_e32 v244, v244
	v_exp_f32_e32 v245, v245
	v_exp_f32_e32 v246, v246
	v_exp_f32_e32 v247, v247
	v_exp_f32_e32 v248, v248
	v_exp_f32_e32 v249, v249
	v_exp_f32_e32 v250, v250
	v_exp_f32_e32 v251, v251
	v_pk_mul_f32 v[236:237], v[236:237], v[6:7]
	v_pk_mul_f32 v[238:239], v[238:239], v[8:9]
	v_pk_mul_f32 v[240:241], v[240:241], v[2:3]
	v_pk_mul_f32 v[242:243], v[242:243], v[4:5]
	v_pk_add_f32 v[244:245], v[244:245], 1.0 op_sel_hi:[1,0]
	v_pk_add_f32 v[246:247], v[246:247], 1.0 op_sel_hi:[1,0]
	v_pk_add_f32 v[248:249], v[248:249], 1.0 op_sel_hi:[1,0]
	v_pk_add_f32 v[250:251], v[250:251], 1.0 op_sel_hi:[1,0]
	v_rcp_f32_e32 v244, v244
	v_rcp_f32_e32 v245, v245
	v_rcp_f32_e32 v246, v246
	v_rcp_f32_e32 v247, v247
	v_rcp_f32_e32 v248, v248
	v_rcp_f32_e32 v249, v249
	v_rcp_f32_e32 v250, v250
	v_rcp_f32_e32 v251, v251
	s_nop 0
	v_pk_mul_f32 v[236:237], v[236:237], v[244:245]
	v_pk_mul_f32 v[238:239], v[238:239], v[246:247]
	v_pk_mul_f32 v[240:241], v[240:241], v[248:249]
	v_pk_mul_f32 v[242:243], v[242:243], v[250:251]
	v_cvt_pk_bf16_f32 v216, v236, v237
	v_cvt_pk_bf16_f32 v217, v238, v239
	v_cvt_pk_bf16_f32 v218, v240, v241
	v_cvt_pk_bf16_f32 v219, v242, v243
	global_store_dwordx4 v[220:221], v[216:219], off
	s_mov_b64 s[66:67], 0x8000
	s_andn2_b64 vcc, exec, s[6:7]
	s_mov_b64 s[6:7], -1
	s_not_b64 s[8:9], s[4:5]
	s_cbranch_vccnz .LBB0_1243
	s_and_b64 vcc, exec, s[8:9]
	s_cbranch_vccnz .LBB0_1242
	s_barrier
	s_branch .LBB0_1242
